# baseline (speedup 1.0000x reference)
; __device__ __forceinline__ void dsa_tile(const Params& p, unsigned char* smem, int tile) {
;     ...
;     __syncthreads();
;     int* myidx = (int*)smem + wid * 256;
;     float* pl = (float*)(smem + 8192) + wid * 1024;
;     unsigned* hist = (unsigned*)(smem + 41984) + wid * 2048;
;     bf16_t* yb = (bf16_t*)(p.ws + WS_Y);
; #pragma unroll 1
;     for (int qi = wid * 2; qi < wid * 2 + 2; ++qi) {
.LBB0_290:
	v_lshlrev_b32_e32 v231, 2, v175
	v_or_b32_e32 v231, 0x10000, v231
	s_lshl_b32 s4, s10, 10
	s_add_i32 s96, s4, 0
	s_mul_i32 s4, s10, 0x1c00
	s_add_i32 s97, s96, s4
	s_lshl_b32 s58, s10, 1
	s_lshl_b64 s[4:5], s[8:9], 22
	s_add_u32 s74, s90, s4
	s_addc_u32 s71, s91, s5
	s_or_b32 s54, s58, 1
	s_barrier
	s_branch .LBB0_292

; template <int SHIFT, int NBITS, bool FIRST>
; __device__ __forceinline__ void radix_pass(const unsigned (&uu)[128], int nreg, unsigned* hist, int lane, unsigned& prefix, int& need) {
;     ...
;     for (int g = 0; g < 8; ++g) {
;         if (g * 16 < nreg) {
; #pragma unroll
;             for (int r = g * 16; r < g * 16 + 16; ++r) {
;                 const unsigned u = uu[r];
;                 const bool match = FIRST ? true : ((u >> (SHIFT + NBITS)) == prefix);
;                 if (match) __hip_atomic_fetch_add(hist + ((u >> SHIFT) & (NBINS - 1)), 1u, __ATOMIC_RELAXED, __HIP_MEMORY_SCOPE_WORKGROUP);
;             }
;         }
;     }
.LBB0_376:
	v_lshrrev_b32_e32 v131, 21, v113
	v_cmp_eq_u32_e32 vcc, s55, v131
	v_lshrrev_b32_e32 v229, 8, v113
	v_and_b32_e32 v229, 0x1ffc, v229
	v_add_u32_e32 v229, s97, v229
	v_cndmask_b32_e32 v229, v231, v229, vcc
	ds_add_u32 v229, v176 offset:41984
	v_lshrrev_b32_e32 v131, 21, v112
	v_cmp_eq_u32_e32 vcc, s55, v131
	v_lshrrev_b32_e32 v229, 8, v112
	v_and_b32_e32 v229, 0x1ffc, v229
	v_add_u32_e32 v229, s97, v229
	v_cndmask_b32_e32 v229, v231, v229, vcc
	ds_add_u32 v229, v176 offset:41984
	v_lshrrev_b32_e32 v131, 21, v111
	v_cmp_eq_u32_e32 vcc, s55, v131
	v_lshrrev_b32_e32 v229, 8, v111
	v_and_b32_e32 v229, 0x1ffc, v229
	v_add_u32_e32 v229, s97, v229
	v_cndmask_b32_e32 v229, v231, v229, vcc
	ds_add_u32 v229, v176 offset:41984
	v_lshrrev_b32_e32 v131, 21, v110
	v_cmp_eq_u32_e32 vcc, s55, v131
	v_lshrrev_b32_e32 v229, 8, v110
	v_and_b32_e32 v229, 0x1ffc, v229
	v_add_u32_e32 v229, s97, v229
	v_cndmask_b32_e32 v229, v231, v229, vcc
	ds_add_u32 v229, v176 offset:41984
	v_lshrrev_b32_e32 v131, 21, v109
	v_cmp_eq_u32_e32 vcc, s55, v131
	v_lshrrev_b32_e32 v229, 8, v109
	v_and_b32_e32 v229, 0x1ffc, v229
	v_add_u32_e32 v229, s97, v229
	v_cndmask_b32_e32 v229, v231, v229, vcc
	ds_add_u32 v229, v176 offset:41984
	v_lshrrev_b32_e32 v131, 21, v108
	v_cmp_eq_u32_e32 vcc, s55, v131
	v_lshrrev_b32_e32 v229, 8, v108
	v_and_b32_e32 v229, 0x1ffc, v229
	v_add_u32_e32 v229, s97, v229
	v_cndmask_b32_e32 v229, v231, v229, vcc
	ds_add_u32 v229, v176 offset:41984
	v_lshrrev_b32_e32 v131, 21, v107
	v_cmp_eq_u32_e32 vcc, s55, v131
	v_lshrrev_b32_e32 v229, 8, v107
	v_and_b32_e32 v229, 0x1ffc, v229
	v_add_u32_e32 v229, s97, v229
	v_cndmask_b32_e32 v229, v231, v229, vcc
	ds_add_u32 v229, v176 offset:41984
	v_lshrrev_b32_e32 v131, 21, v106
	v_cmp_eq_u32_e32 vcc, s55, v131
	v_lshrrev_b32_e32 v229, 8, v106
	v_and_b32_e32 v229, 0x1ffc, v229
	v_add_u32_e32 v229, s97, v229
	v_cndmask_b32_e32 v229, v231, v229, vcc
	ds_add_u32 v229, v176 offset:41984
	v_lshrrev_b32_e32 v131, 21, v105
	v_cmp_eq_u32_e32 vcc, s55, v131
	v_lshrrev_b32_e32 v229, 8, v105
	v_and_b32_e32 v229, 0x1ffc, v229
	v_add_u32_e32 v229, s97, v229
	v_cndmask_b32_e32 v229, v231, v229, vcc
	ds_add_u32 v229, v176 offset:41984
	v_lshrrev_b32_e32 v131, 21, v104
	v_cmp_eq_u32_e32 vcc, s55, v131
	v_lshrrev_b32_e32 v229, 8, v104
	v_and_b32_e32 v229, 0x1ffc, v229
	v_add_u32_e32 v229, s97, v229
	v_cndmask_b32_e32 v229, v231, v229, vcc
	ds_add_u32 v229, v176 offset:41984
	v_lshrrev_b32_e32 v131, 21, v103
	v_cmp_eq_u32_e32 vcc, s55, v131
	v_lshrrev_b32_e32 v229, 8, v103
	v_and_b32_e32 v229, 0x1ffc, v229
	v_add_u32_e32 v229, s97, v229
	v_cndmask_b32_e32 v229, v231, v229, vcc
	ds_add_u32 v229, v176 offset:41984
	v_lshrrev_b32_e32 v131, 21, v102
	v_cmp_eq_u32_e32 vcc, s55, v131
	v_lshrrev_b32_e32 v229, 8, v102
	v_and_b32_e32 v229, 0x1ffc, v229
	v_add_u32_e32 v229, s97, v229
	v_cndmask_b32_e32 v229, v231, v229, vcc
	ds_add_u32 v229, v176 offset:41984
	v_lshrrev_b32_e32 v131, 21, v101
	v_cmp_eq_u32_e32 vcc, s55, v131
	v_lshrrev_b32_e32 v229, 8, v101
	v_and_b32_e32 v229, 0x1ffc, v229
	v_add_u32_e32 v229, s97, v229
	v_cndmask_b32_e32 v229, v231, v229, vcc
	ds_add_u32 v229, v176 offset:41984
	v_lshrrev_b32_e32 v131, 21, v100
	v_cmp_eq_u32_e32 vcc, s55, v131
	v_lshrrev_b32_e32 v229, 8, v100
	v_and_b32_e32 v229, 0x1ffc, v229
	v_add_u32_e32 v229, s97, v229
	v_cndmask_b32_e32 v229, v231, v229, vcc
	ds_add_u32 v229, v176 offset:41984
	v_lshrrev_b32_e32 v131, 21, v99
	v_cmp_eq_u32_e32 vcc, s55, v131
	v_lshrrev_b32_e32 v229, 8, v99
	v_and_b32_e32 v229, 0x1ffc, v229
	v_add_u32_e32 v229, s97, v229
	v_cndmask_b32_e32 v229, v231, v229, vcc
	ds_add_u32 v229, v176 offset:41984
	v_lshrrev_b32_e32 v131, 21, v97
	v_cmp_eq_u32_e32 vcc, s55, v131
	v_lshrrev_b32_e32 v229, 8, v97
	v_and_b32_e32 v229, 0x1ffc, v229
	v_add_u32_e32 v229, s97, v229
	v_cndmask_b32_e32 v229, v231, v229, vcc
	ds_add_u32 v229, v176 offset:41984
	v_cndmask_b32_e64 v131, 0, 1, s[28:29]
	v_cmp_ne_u32_e64 s[26:27], 1, v131
	s_andn2_b64 vcc, exec, s[28:29]
	s_cbranch_vccnz .LBB0_344
.LBB0_409:
	v_lshrrev_b32_e32 v131, 21, v98
	v_cmp_eq_u32_e32 vcc, s55, v131
	v_lshrrev_b32_e32 v229, 8, v98
	v_and_b32_e32 v229, 0x1ffc, v229
	v_add_u32_e32 v229, s97, v229
	v_cndmask_b32_e32 v229, v231, v229, vcc
	ds_add_u32 v229, v176 offset:41984
	v_lshrrev_b32_e32 v131, 21, v96
	v_cmp_eq_u32_e32 vcc, s55, v131
	v_lshrrev_b32_e32 v229, 8, v96
	v_and_b32_e32 v229, 0x1ffc, v229
	v_add_u32_e32 v229, s97, v229
	v_cndmask_b32_e32 v229, v231, v229, vcc
	ds_add_u32 v229, v176 offset:41984
	v_lshrrev_b32_e32 v131, 21, v95
	v_cmp_eq_u32_e32 vcc, s55, v131
	v_lshrrev_b32_e32 v229, 8, v95
	v_and_b32_e32 v229, 0x1ffc, v229
	v_add_u32_e32 v229, s97, v229
	v_cndmask_b32_e32 v229, v231, v229, vcc
	ds_add_u32 v229, v176 offset:41984
	v_lshrrev_b32_e32 v131, 21, v94
	v_cmp_eq_u32_e32 vcc, s55, v131
	v_lshrrev_b32_e32 v229, 8, v94
	v_and_b32_e32 v229, 0x1ffc, v229
	v_add_u32_e32 v229, s97, v229
	v_cndmask_b32_e32 v229, v231, v229, vcc
	ds_add_u32 v229, v176 offset:41984
	v_lshrrev_b32_e32 v131, 21, v93
	v_cmp_eq_u32_e32 vcc, s55, v131
	v_lshrrev_b32_e32 v229, 8, v93
	v_and_b32_e32 v229, 0x1ffc, v229
	v_add_u32_e32 v229, s97, v229
	v_cndmask_b32_e32 v229, v231, v229, vcc
	ds_add_u32 v229, v176 offset:41984
	v_lshrrev_b32_e32 v131, 21, v92
	v_cmp_eq_u32_e32 vcc, s55, v131
	v_lshrrev_b32_e32 v229, 8, v92
	v_and_b32_e32 v229, 0x1ffc, v229
	v_add_u32_e32 v229, s97, v229
	v_cndmask_b32_e32 v229, v231, v229, vcc
	ds_add_u32 v229, v176 offset:41984
	v_lshrrev_b32_e32 v131, 21, v91
	v_cmp_eq_u32_e32 vcc, s55, v131
	v_lshrrev_b32_e32 v229, 8, v91
	v_and_b32_e32 v229, 0x1ffc, v229
	v_add_u32_e32 v229, s97, v229
; template <int SHIFT, int NBITS, bool FIRST>
; __device__ __forceinline__ void radix_pass(const unsigned (&uu)[128], int nreg, unsigned* hist, int lane, unsigned& prefix, int& need) {
;     ...
;     for (int g = 0; g < 8; ++g) {
;         if (g * 16 < nreg) {
; #pragma unroll
;             for (int r = g * 16; r < g * 16 + 16; ++r) {
;                 const unsigned u = uu[r];
;                 const bool match = FIRST ? true : ((u >> (SHIFT + NBITS)) == prefix);
;                 if (match) __hip_atomic_fetch_add(hist + ((u >> SHIFT) & (NBINS - 1)), 1u, __ATOMIC_RELAXED, __HIP_MEMORY_SCOPE_WORKGROUP);
;             }
;         }
;     }
	v_cndmask_b32_e32 v229, v231, v229, vcc
	ds_add_u32 v229, v176 offset:41984
	v_lshrrev_b32_e32 v131, 21, v90
	v_cmp_eq_u32_e32 vcc, s55, v131
	v_lshrrev_b32_e32 v229, 8, v90
	v_and_b32_e32 v229, 0x1ffc, v229
	v_add_u32_e32 v229, s97, v229
	v_cndmask_b32_e32 v229, v231, v229, vcc
	ds_add_u32 v229, v176 offset:41984
	v_lshrrev_b32_e32 v131, 21, v89
	v_cmp_eq_u32_e32 vcc, s55, v131
	v_lshrrev_b32_e32 v229, 8, v89
	v_and_b32_e32 v229, 0x1ffc, v229
	v_add_u32_e32 v229, s97, v229
	v_cndmask_b32_e32 v229, v231, v229, vcc
	ds_add_u32 v229, v176 offset:41984
	v_lshrrev_b32_e32 v131, 21, v88
	v_cmp_eq_u32_e32 vcc, s55, v131
	v_lshrrev_b32_e32 v229, 8, v88
	v_and_b32_e32 v229, 0x1ffc, v229
	v_add_u32_e32 v229, s97, v229
	v_cndmask_b32_e32 v229, v231, v229, vcc
	ds_add_u32 v229, v176 offset:41984
	v_lshrrev_b32_e32 v131, 21, v87
	v_cmp_eq_u32_e32 vcc, s55, v131
	v_lshrrev_b32_e32 v229, 8, v87
	v_and_b32_e32 v229, 0x1ffc, v229
	v_add_u32_e32 v229, s97, v229
	v_cndmask_b32_e32 v229, v231, v229, vcc
	ds_add_u32 v229, v176 offset:41984
	v_lshrrev_b32_e32 v131, 21, v86
	v_cmp_eq_u32_e32 vcc, s55, v131
	v_lshrrev_b32_e32 v229, 8, v86
	v_and_b32_e32 v229, 0x1ffc, v229
	v_add_u32_e32 v229, s97, v229
	v_cndmask_b32_e32 v229, v231, v229, vcc
	ds_add_u32 v229, v176 offset:41984
	v_lshrrev_b32_e32 v131, 21, v85
	v_cmp_eq_u32_e32 vcc, s55, v131
	v_lshrrev_b32_e32 v229, 8, v85
	v_and_b32_e32 v229, 0x1ffc, v229
	v_add_u32_e32 v229, s97, v229
	v_cndmask_b32_e32 v229, v231, v229, vcc
	ds_add_u32 v229, v176 offset:41984
	v_lshrrev_b32_e32 v131, 21, v84
	v_cmp_eq_u32_e32 vcc, s55, v131
	v_lshrrev_b32_e32 v229, 8, v84
	v_and_b32_e32 v229, 0x1ffc, v229
	v_add_u32_e32 v229, s97, v229
	v_cndmask_b32_e32 v229, v231, v229, vcc
	ds_add_u32 v229, v176 offset:41984
	v_lshrrev_b32_e32 v131, 21, v83
	v_cmp_eq_u32_e32 vcc, s55, v131
	v_lshrrev_b32_e32 v229, 8, v83
	v_and_b32_e32 v229, 0x1ffc, v229
	v_add_u32_e32 v229, s97, v229
	v_cndmask_b32_e32 v229, v231, v229, vcc
	ds_add_u32 v229, v176 offset:41984
	v_lshrrev_b32_e32 v131, 21, v79
	v_cmp_eq_u32_e32 vcc, s55, v131
	v_lshrrev_b32_e32 v229, 8, v79
	v_and_b32_e32 v229, 0x1ffc, v229
	v_add_u32_e32 v229, s97, v229
	v_cndmask_b32_e32 v229, v231, v229, vcc
	ds_add_u32 v229, v176 offset:41984
	v_cndmask_b32_e64 v131, 0, 1, s[30:31]
	v_cmp_ne_u32_e64 s[28:29], 1, v131
	s_andn2_b64 vcc, exec, s[30:31]
	s_cbranch_vccnz .LBB0_345
.LBB0_442:
	v_lshrrev_b32_e32 v131, 21, v82
	v_cmp_eq_u32_e32 vcc, s55, v131
	v_lshrrev_b32_e32 v229, 8, v82
	v_and_b32_e32 v229, 0x1ffc, v229
	v_add_u32_e32 v229, s97, v229
	v_cndmask_b32_e32 v229, v231, v229, vcc
	ds_add_u32 v229, v176 offset:41984
	v_lshrrev_b32_e32 v131, 21, v81
	v_cmp_eq_u32_e32 vcc, s55, v131
	v_lshrrev_b32_e32 v229, 8, v81
	v_and_b32_e32 v229, 0x1ffc, v229
	v_add_u32_e32 v229, s97, v229
	v_cndmask_b32_e32 v229, v231, v229, vcc
	ds_add_u32 v229, v176 offset:41984
	v_lshrrev_b32_e32 v131, 21, v80
	v_cmp_eq_u32_e32 vcc, s55, v131
	v_lshrrev_b32_e32 v229, 8, v80
	v_and_b32_e32 v229, 0x1ffc, v229
	v_add_u32_e32 v229, s97, v229
	v_cndmask_b32_e32 v229, v231, v229, vcc
	ds_add_u32 v229, v176 offset:41984
	v_lshrrev_b32_e32 v131, 21, v78
	v_cmp_eq_u32_e32 vcc, s55, v131
	v_lshrrev_b32_e32 v229, 8, v78
	v_and_b32_e32 v229, 0x1ffc, v229
	v_add_u32_e32 v229, s97, v229
	v_cndmask_b32_e32 v229, v231, v229, vcc
	ds_add_u32 v229, v176 offset:41984
	v_lshrrev_b32_e32 v131, 21, v77
	v_cmp_eq_u32_e32 vcc, s55, v131
	v_lshrrev_b32_e32 v229, 8, v77
	v_and_b32_e32 v229, 0x1ffc, v229
	v_add_u32_e32 v229, s97, v229
	v_cndmask_b32_e32 v229, v231, v229, vcc
	ds_add_u32 v229, v176 offset:41984
	v_lshrrev_b32_e32 v131, 21, v76
	v_cmp_eq_u32_e32 vcc, s55, v131
	v_lshrrev_b32_e32 v229, 8, v76
	v_and_b32_e32 v229, 0x1ffc, v229
	v_add_u32_e32 v229, s97, v229
	v_cndmask_b32_e32 v229, v231, v229, vcc
	ds_add_u32 v229, v176 offset:41984
	v_lshrrev_b32_e32 v131, 21, v75
	v_cmp_eq_u32_e32 vcc, s55, v131
	v_lshrrev_b32_e32 v229, 8, v75
	v_and_b32_e32 v229, 0x1ffc, v229
	v_add_u32_e32 v229, s97, v229
	v_cndmask_b32_e32 v229, v231, v229, vcc
	ds_add_u32 v229, v176 offset:41984
	v_lshrrev_b32_e32 v131, 21, v74
	v_cmp_eq_u32_e32 vcc, s55, v131
	v_lshrrev_b32_e32 v229, 8, v74
	v_and_b32_e32 v229, 0x1ffc, v229
	v_add_u32_e32 v229, s97, v229
	v_cndmask_b32_e32 v229, v231, v229, vcc
	ds_add_u32 v229, v176 offset:41984
	v_lshrrev_b32_e32 v131, 21, v73
	v_cmp_eq_u32_e32 vcc, s55, v131
	v_lshrrev_b32_e32 v229, 8, v73
	v_and_b32_e32 v229, 0x1ffc, v229
	v_add_u32_e32 v229, s97, v229
	v_cndmask_b32_e32 v229, v231, v229, vcc
	ds_add_u32 v229, v176 offset:41984
	v_lshrrev_b32_e32 v131, 21, v72
	v_cmp_eq_u32_e32 vcc, s55, v131
	v_lshrrev_b32_e32 v229, 8, v72
	v_and_b32_e32 v229, 0x1ffc, v229
	v_add_u32_e32 v229, s97, v229
	v_cndmask_b32_e32 v229, v231, v229, vcc
	ds_add_u32 v229, v176 offset:41984
	v_lshrrev_b32_e32 v131, 21, v71
	v_cmp_eq_u32_e32 vcc, s55, v131
	v_lshrrev_b32_e32 v229, 8, v71
	v_and_b32_e32 v229, 0x1ffc, v229
	v_add_u32_e32 v229, s97, v229
	v_cndmask_b32_e32 v229, v231, v229, vcc
	ds_add_u32 v229, v176 offset:41984
	v_lshrrev_b32_e32 v131, 21, v70
	v_cmp_eq_u32_e32 vcc, s55, v131
	v_lshrrev_b32_e32 v229, 8, v70
	v_and_b32_e32 v229, 0x1ffc, v229
	v_add_u32_e32 v229, s97, v229
	v_cndmask_b32_e32 v229, v231, v229, vcc
	ds_add_u32 v229, v176 offset:41984
	v_lshrrev_b32_e32 v131, 21, v69
	v_cmp_eq_u32_e32 vcc, s55, v131
	v_lshrrev_b32_e32 v229, 8, v69
	v_and_b32_e32 v229, 0x1ffc, v229
	v_add_u32_e32 v229, s97, v229
	v_cndmask_b32_e32 v229, v231, v229, vcc
	ds_add_u32 v229, v176 offset:41984
	v_lshrrev_b32_e32 v131, 21, v68
	v_cmp_eq_u32_e32 vcc, s55, v131
	v_lshrrev_b32_e32 v229, 8, v68
	v_and_b32_e32 v229, 0x1ffc, v229
	v_add_u32_e32 v229, s97, v229
	v_cndmask_b32_e32 v229, v231, v229, vcc
	ds_add_u32 v229, v176 offset:41984
	v_lshrrev_b32_e32 v131, 21, v67
	v_cmp_eq_u32_e32 vcc, s55, v131
	v_lshrrev_b32_e32 v229, 8, v67
	v_and_b32_e32 v229, 0x1ffc, v229
	v_add_u32_e32 v229, s97, v229
	v_cndmask_b32_e32 v229, v231, v229, vcc
	ds_add_u32 v229, v176 offset:41984
	v_lshrrev_b32_e32 v131, 21, v65
	v_cmp_eq_u32_e32 vcc, s55, v131
	v_lshrrev_b32_e32 v229, 8, v65
	v_and_b32_e32 v229, 0x1ffc, v229
	v_add_u32_e32 v229, s97, v229
	v_cndmask_b32_e32 v229, v231, v229, vcc
	ds_add_u32 v229, v176 offset:41984
	v_cndmask_b32_e64 v131, 0, 1, s[34:35]
	v_cmp_ne_u32_e64 s[30:31], 1, v131
	s_andn2_b64 vcc, exec, s[34:35]
	s_cbranch_vccnz .LBB0_346
; template <int SHIFT, int NBITS, bool FIRST>
; __device__ __forceinline__ void radix_pass(const unsigned (&uu)[128], int nreg, unsigned* hist, int lane, unsigned& prefix, int& need) {
;     ...
;     for (int g = 0; g < 8; ++g) {
;         if (g * 16 < nreg) {
; #pragma unroll
;             for (int r = g * 16; r < g * 16 + 16; ++r) {
;                 const unsigned u = uu[r];
;                 const bool match = FIRST ? true : ((u >> (SHIFT + NBITS)) == prefix);
;                 if (match) __hip_atomic_fetch_add(hist + ((u >> SHIFT) & (NBINS - 1)), 1u, __ATOMIC_RELAXED, __HIP_MEMORY_SCOPE_WORKGROUP);
;             }
;         }
;     }
.LBB0_475:
	v_lshrrev_b32_e32 v131, 21, v66
	v_cmp_eq_u32_e32 vcc, s55, v131
	v_lshrrev_b32_e32 v229, 8, v66
	v_and_b32_e32 v229, 0x1ffc, v229
	v_add_u32_e32 v229, s97, v229
	v_cndmask_b32_e32 v229, v231, v229, vcc
	ds_add_u32 v229, v176 offset:41984
	v_lshrrev_b32_e32 v131, 21, v64
	v_cmp_eq_u32_e32 vcc, s55, v131
	v_lshrrev_b32_e32 v229, 8, v64
	v_and_b32_e32 v229, 0x1ffc, v229
	v_add_u32_e32 v229, s97, v229
	v_cndmask_b32_e32 v229, v231, v229, vcc
	ds_add_u32 v229, v176 offset:41984
	v_lshrrev_b32_e32 v131, 21, v63
	v_cmp_eq_u32_e32 vcc, s55, v131
	v_lshrrev_b32_e32 v229, 8, v63
	v_and_b32_e32 v229, 0x1ffc, v229
	v_add_u32_e32 v229, s97, v229
	v_cndmask_b32_e32 v229, v231, v229, vcc
	ds_add_u32 v229, v176 offset:41984
	v_lshrrev_b32_e32 v131, 21, v62
	v_cmp_eq_u32_e32 vcc, s55, v131
	v_lshrrev_b32_e32 v229, 8, v62
	v_and_b32_e32 v229, 0x1ffc, v229
	v_add_u32_e32 v229, s97, v229
	v_cndmask_b32_e32 v229, v231, v229, vcc
	ds_add_u32 v229, v176 offset:41984
	v_lshrrev_b32_e32 v131, 21, v61
	v_cmp_eq_u32_e32 vcc, s55, v131
	v_lshrrev_b32_e32 v229, 8, v61
	v_and_b32_e32 v229, 0x1ffc, v229
	v_add_u32_e32 v229, s97, v229
	v_cndmask_b32_e32 v229, v231, v229, vcc
	ds_add_u32 v229, v176 offset:41984
	v_lshrrev_b32_e32 v131, 21, v60
	v_cmp_eq_u32_e32 vcc, s55, v131
	v_lshrrev_b32_e32 v229, 8, v60
	v_and_b32_e32 v229, 0x1ffc, v229
	v_add_u32_e32 v229, s97, v229
	v_cndmask_b32_e32 v229, v231, v229, vcc
	ds_add_u32 v229, v176 offset:41984
	v_lshrrev_b32_e32 v131, 21, v59
	v_cmp_eq_u32_e32 vcc, s55, v131
	v_lshrrev_b32_e32 v229, 8, v59
	v_and_b32_e32 v229, 0x1ffc, v229
	v_add_u32_e32 v229, s97, v229
	v_cndmask_b32_e32 v229, v231, v229, vcc
	ds_add_u32 v229, v176 offset:41984
	v_lshrrev_b32_e32 v131, 21, v58
	v_cmp_eq_u32_e32 vcc, s55, v131
	v_lshrrev_b32_e32 v229, 8, v58
	v_and_b32_e32 v229, 0x1ffc, v229
	v_add_u32_e32 v229, s97, v229
	v_cndmask_b32_e32 v229, v231, v229, vcc
	ds_add_u32 v229, v176 offset:41984
	v_lshrrev_b32_e32 v131, 21, v57
	v_cmp_eq_u32_e32 vcc, s55, v131
	v_lshrrev_b32_e32 v229, 8, v57
	v_and_b32_e32 v229, 0x1ffc, v229
	v_add_u32_e32 v229, s97, v229
	v_cndmask_b32_e32 v229, v231, v229, vcc
	ds_add_u32 v229, v176 offset:41984
	v_lshrrev_b32_e32 v131, 21, v56
	v_cmp_eq_u32_e32 vcc, s55, v131
	v_lshrrev_b32_e32 v229, 8, v56
	v_and_b32_e32 v229, 0x1ffc, v229
	v_add_u32_e32 v229, s97, v229
	v_cndmask_b32_e32 v229, v231, v229, vcc
	ds_add_u32 v229, v176 offset:41984
	v_lshrrev_b32_e32 v131, 21, v55
	v_cmp_eq_u32_e32 vcc, s55, v131
	v_lshrrev_b32_e32 v229, 8, v55
	v_and_b32_e32 v229, 0x1ffc, v229
	v_add_u32_e32 v229, s97, v229
	v_cndmask_b32_e32 v229, v231, v229, vcc
	ds_add_u32 v229, v176 offset:41984
	v_lshrrev_b32_e32 v131, 21, v54
	v_cmp_eq_u32_e32 vcc, s55, v131
	v_lshrrev_b32_e32 v229, 8, v54
	v_and_b32_e32 v229, 0x1ffc, v229
	v_add_u32_e32 v229, s97, v229
	v_cndmask_b32_e32 v229, v231, v229, vcc
	ds_add_u32 v229, v176 offset:41984
	v_lshrrev_b32_e32 v131, 21, v53
	v_cmp_eq_u32_e32 vcc, s55, v131
	v_lshrrev_b32_e32 v229, 8, v53
	v_and_b32_e32 v229, 0x1ffc, v229
	v_add_u32_e32 v229, s97, v229
	v_cndmask_b32_e32 v229, v231, v229, vcc
	ds_add_u32 v229, v176 offset:41984
	v_lshrrev_b32_e32 v131, 21, v52
	v_cmp_eq_u32_e32 vcc, s55, v131
	v_lshrrev_b32_e32 v229, 8, v52
	v_and_b32_e32 v229, 0x1ffc, v229
	v_add_u32_e32 v229, s97, v229
	v_cndmask_b32_e32 v229, v231, v229, vcc
	ds_add_u32 v229, v176 offset:41984
	v_lshrrev_b32_e32 v131, 21, v51
	v_cmp_eq_u32_e32 vcc, s55, v131
	v_lshrrev_b32_e32 v229, 8, v51
	v_and_b32_e32 v229, 0x1ffc, v229
	v_add_u32_e32 v229, s97, v229
	v_cndmask_b32_e32 v229, v231, v229, vcc
	ds_add_u32 v229, v176 offset:41984
	v_lshrrev_b32_e32 v131, 21, v47
	v_cmp_eq_u32_e32 vcc, s55, v131
	v_lshrrev_b32_e32 v229, 8, v47
	v_and_b32_e32 v229, 0x1ffc, v229
	v_add_u32_e32 v229, s97, v229
	v_cndmask_b32_e32 v229, v231, v229, vcc
	ds_add_u32 v229, v176 offset:41984
	v_cndmask_b32_e64 v131, 0, 1, s[36:37]
	v_cmp_ne_u32_e64 s[34:35], 1, v131
	s_andn2_b64 vcc, exec, s[36:37]
	s_cbranch_vccnz .LBB0_347
.LBB0_508:
	v_lshrrev_b32_e32 v131, 21, v50
	v_cmp_eq_u32_e32 vcc, s55, v131
	v_lshrrev_b32_e32 v229, 8, v50
	v_and_b32_e32 v229, 0x1ffc, v229
	v_add_u32_e32 v229, s97, v229
	v_cndmask_b32_e32 v229, v231, v229, vcc
	ds_add_u32 v229, v176 offset:41984
	v_lshrrev_b32_e32 v131, 21, v49
	v_cmp_eq_u32_e32 vcc, s55, v131
	v_lshrrev_b32_e32 v229, 8, v49
	v_and_b32_e32 v229, 0x1ffc, v229
	v_add_u32_e32 v229, s97, v229
	v_cndmask_b32_e32 v229, v231, v229, vcc
	ds_add_u32 v229, v176 offset:41984
	v_lshrrev_b32_e32 v131, 21, v48
	v_cmp_eq_u32_e32 vcc, s55, v131
	v_lshrrev_b32_e32 v229, 8, v48
	v_and_b32_e32 v229, 0x1ffc, v229
	v_add_u32_e32 v229, s97, v229
	v_cndmask_b32_e32 v229, v231, v229, vcc
	ds_add_u32 v229, v176 offset:41984
	v_lshrrev_b32_e32 v131, 21, v46
	v_cmp_eq_u32_e32 vcc, s55, v131
	v_lshrrev_b32_e32 v229, 8, v46
	v_and_b32_e32 v229, 0x1ffc, v229
	v_add_u32_e32 v229, s97, v229
	v_cndmask_b32_e32 v229, v231, v229, vcc
	ds_add_u32 v229, v176 offset:41984
	v_lshrrev_b32_e32 v131, 21, v45
	v_cmp_eq_u32_e32 vcc, s55, v131
	v_lshrrev_b32_e32 v229, 8, v45
	v_and_b32_e32 v229, 0x1ffc, v229
	v_add_u32_e32 v229, s97, v229
	v_cndmask_b32_e32 v229, v231, v229, vcc
	ds_add_u32 v229, v176 offset:41984
	v_lshrrev_b32_e32 v131, 21, v44
	v_cmp_eq_u32_e32 vcc, s55, v131
	v_lshrrev_b32_e32 v229, 8, v44
	v_and_b32_e32 v229, 0x1ffc, v229
	v_add_u32_e32 v229, s97, v229
	v_cndmask_b32_e32 v229, v231, v229, vcc
	ds_add_u32 v229, v176 offset:41984
	v_lshrrev_b32_e32 v131, 21, v43
	v_cmp_eq_u32_e32 vcc, s55, v131
	v_lshrrev_b32_e32 v229, 8, v43
	v_and_b32_e32 v229, 0x1ffc, v229
	v_add_u32_e32 v229, s97, v229
	v_cndmask_b32_e32 v229, v231, v229, vcc
; template <int SHIFT, int NBITS, bool FIRST>
; __device__ __forceinline__ void radix_pass(const unsigned (&uu)[128], int nreg, unsigned* hist, int lane, unsigned& prefix, int& need) {
;     ...
;     for (int g = 0; g < 8; ++g) {
;         if (g * 16 < nreg) {
; #pragma unroll
;             for (int r = g * 16; r < g * 16 + 16; ++r) {
;                 const unsigned u = uu[r];
;                 const bool match = FIRST ? true : ((u >> (SHIFT + NBITS)) == prefix);
;                 if (match) __hip_atomic_fetch_add(hist + ((u >> SHIFT) & (NBINS - 1)), 1u, __ATOMIC_RELAXED, __HIP_MEMORY_SCOPE_WORKGROUP);
;             }
;         }
;     }
	ds_add_u32 v229, v176 offset:41984
	v_lshrrev_b32_e32 v131, 21, v42
	v_cmp_eq_u32_e32 vcc, s55, v131
	v_lshrrev_b32_e32 v229, 8, v42
	v_and_b32_e32 v229, 0x1ffc, v229
	v_add_u32_e32 v229, s97, v229
	v_cndmask_b32_e32 v229, v231, v229, vcc
	ds_add_u32 v229, v176 offset:41984
	v_lshrrev_b32_e32 v131, 21, v41
	v_cmp_eq_u32_e32 vcc, s55, v131
	v_lshrrev_b32_e32 v229, 8, v41
	v_and_b32_e32 v229, 0x1ffc, v229
	v_add_u32_e32 v229, s97, v229
	v_cndmask_b32_e32 v229, v231, v229, vcc
	ds_add_u32 v229, v176 offset:41984
	v_lshrrev_b32_e32 v131, 21, v40
	v_cmp_eq_u32_e32 vcc, s55, v131
	v_lshrrev_b32_e32 v229, 8, v40
	v_and_b32_e32 v229, 0x1ffc, v229
	v_add_u32_e32 v229, s97, v229
	v_cndmask_b32_e32 v229, v231, v229, vcc
	ds_add_u32 v229, v176 offset:41984
	v_lshrrev_b32_e32 v131, 21, v39
	v_cmp_eq_u32_e32 vcc, s55, v131
	v_lshrrev_b32_e32 v229, 8, v39
	v_and_b32_e32 v229, 0x1ffc, v229
	v_add_u32_e32 v229, s97, v229
	v_cndmask_b32_e32 v229, v231, v229, vcc
	ds_add_u32 v229, v176 offset:41984
	v_lshrrev_b32_e32 v131, 21, v38
	v_cmp_eq_u32_e32 vcc, s55, v131
	v_lshrrev_b32_e32 v229, 8, v38
	v_and_b32_e32 v229, 0x1ffc, v229
	v_add_u32_e32 v229, s97, v229
	v_cndmask_b32_e32 v229, v231, v229, vcc
	ds_add_u32 v229, v176 offset:41984
	v_lshrrev_b32_e32 v131, 21, v37
	v_cmp_eq_u32_e32 vcc, s55, v131
	v_lshrrev_b32_e32 v229, 8, v37
	v_and_b32_e32 v229, 0x1ffc, v229
	v_add_u32_e32 v229, s97, v229
	v_cndmask_b32_e32 v229, v231, v229, vcc
	ds_add_u32 v229, v176 offset:41984
	v_lshrrev_b32_e32 v131, 21, v36
	v_cmp_eq_u32_e32 vcc, s55, v131
	v_lshrrev_b32_e32 v229, 8, v36
	v_and_b32_e32 v229, 0x1ffc, v229
	v_add_u32_e32 v229, s97, v229
	v_cndmask_b32_e32 v229, v231, v229, vcc
	ds_add_u32 v229, v176 offset:41984
	v_lshrrev_b32_e32 v131, 21, v35
	v_cmp_eq_u32_e32 vcc, s55, v131
	v_lshrrev_b32_e32 v229, 8, v35
	v_and_b32_e32 v229, 0x1ffc, v229
	v_add_u32_e32 v229, s97, v229
	v_cndmask_b32_e32 v229, v231, v229, vcc
	ds_add_u32 v229, v176 offset:41984
	v_lshrrev_b32_e32 v131, 21, v33
	v_cmp_eq_u32_e32 vcc, s55, v131
	v_lshrrev_b32_e32 v229, 8, v33
	v_and_b32_e32 v229, 0x1ffc, v229
	v_add_u32_e32 v229, s97, v229
	v_cndmask_b32_e32 v229, v231, v229, vcc
	ds_add_u32 v229, v176 offset:41984
	v_cndmask_b32_e64 v131, 0, 1, s[38:39]
	v_cmp_ne_u32_e64 s[36:37], 1, v131
	s_andn2_b64 vcc, exec, s[38:39]
	s_cbranch_vccnz .LBB0_348
.LBB0_541:
	v_lshrrev_b32_e32 v131, 21, v34
	v_cmp_eq_u32_e32 vcc, s55, v131
	v_lshrrev_b32_e32 v229, 8, v34
	v_and_b32_e32 v229, 0x1ffc, v229
	v_add_u32_e32 v229, s97, v229
	v_cndmask_b32_e32 v229, v231, v229, vcc
	ds_add_u32 v229, v176 offset:41984
	v_lshrrev_b32_e32 v131, 21, v32
	v_cmp_eq_u32_e32 vcc, s55, v131
	v_lshrrev_b32_e32 v229, 8, v32
	v_and_b32_e32 v229, 0x1ffc, v229
	v_add_u32_e32 v229, s97, v229
	v_cndmask_b32_e32 v229, v231, v229, vcc
	ds_add_u32 v229, v176 offset:41984
	v_lshrrev_b32_e32 v131, 21, v31
	v_cmp_eq_u32_e32 vcc, s55, v131
	v_lshrrev_b32_e32 v229, 8, v31
	v_and_b32_e32 v229, 0x1ffc, v229
	v_add_u32_e32 v229, s97, v229
	v_cndmask_b32_e32 v229, v231, v229, vcc
	ds_add_u32 v229, v176 offset:41984
	v_lshrrev_b32_e32 v131, 21, v30
	v_cmp_eq_u32_e32 vcc, s55, v131
	v_lshrrev_b32_e32 v229, 8, v30
	v_and_b32_e32 v229, 0x1ffc, v229
	v_add_u32_e32 v229, s97, v229
	v_cndmask_b32_e32 v229, v231, v229, vcc
	ds_add_u32 v229, v176 offset:41984
	v_lshrrev_b32_e32 v131, 21, v29
	v_cmp_eq_u32_e32 vcc, s55, v131
	v_lshrrev_b32_e32 v229, 8, v29
	v_and_b32_e32 v229, 0x1ffc, v229
	v_add_u32_e32 v229, s97, v229
	v_cndmask_b32_e32 v229, v231, v229, vcc
	ds_add_u32 v229, v176 offset:41984
	v_lshrrev_b32_e32 v131, 21, v28
	v_cmp_eq_u32_e32 vcc, s55, v131
	v_lshrrev_b32_e32 v229, 8, v28
	v_and_b32_e32 v229, 0x1ffc, v229
	v_add_u32_e32 v229, s97, v229
	v_cndmask_b32_e32 v229, v231, v229, vcc
	ds_add_u32 v229, v176 offset:41984
	v_lshrrev_b32_e32 v131, 21, v27
	v_cmp_eq_u32_e32 vcc, s55, v131
	v_lshrrev_b32_e32 v229, 8, v27
	v_and_b32_e32 v229, 0x1ffc, v229
	v_add_u32_e32 v229, s97, v229
	v_cndmask_b32_e32 v229, v231, v229, vcc
	ds_add_u32 v229, v176 offset:41984
	v_lshrrev_b32_e32 v131, 21, v26
	v_cmp_eq_u32_e32 vcc, s55, v131
	v_lshrrev_b32_e32 v229, 8, v26
	v_and_b32_e32 v229, 0x1ffc, v229
	v_add_u32_e32 v229, s97, v229
	v_cndmask_b32_e32 v229, v231, v229, vcc
	ds_add_u32 v229, v176 offset:41984
	v_lshrrev_b32_e32 v131, 21, v25
	v_cmp_eq_u32_e32 vcc, s55, v131
	v_lshrrev_b32_e32 v229, 8, v25
	v_and_b32_e32 v229, 0x1ffc, v229
	v_add_u32_e32 v229, s97, v229
	v_cndmask_b32_e32 v229, v231, v229, vcc
	ds_add_u32 v229, v176 offset:41984
	v_lshrrev_b32_e32 v131, 21, v24
	v_cmp_eq_u32_e32 vcc, s55, v131
	v_lshrrev_b32_e32 v229, 8, v24
	v_and_b32_e32 v229, 0x1ffc, v229
	v_add_u32_e32 v229, s97, v229
	v_cndmask_b32_e32 v229, v231, v229, vcc
	ds_add_u32 v229, v176 offset:41984
	v_lshrrev_b32_e32 v131, 21, v23
	v_cmp_eq_u32_e32 vcc, s55, v131
	v_lshrrev_b32_e32 v229, 8, v23
	v_and_b32_e32 v229, 0x1ffc, v229
	v_add_u32_e32 v229, s97, v229
	v_cndmask_b32_e32 v229, v231, v229, vcc
	ds_add_u32 v229, v176 offset:41984
	v_lshrrev_b32_e32 v131, 21, v22
	v_cmp_eq_u32_e32 vcc, s55, v131
	v_lshrrev_b32_e32 v229, 8, v22
	v_and_b32_e32 v229, 0x1ffc, v229
	v_add_u32_e32 v229, s97, v229
	v_cndmask_b32_e32 v229, v231, v229, vcc
	ds_add_u32 v229, v176 offset:41984
	v_lshrrev_b32_e32 v131, 21, v21
	v_cmp_eq_u32_e32 vcc, s55, v131
	v_lshrrev_b32_e32 v229, 8, v21
	v_and_b32_e32 v229, 0x1ffc, v229
	v_add_u32_e32 v229, s97, v229
	v_cndmask_b32_e32 v229, v231, v229, vcc
	ds_add_u32 v229, v176 offset:41984
	v_lshrrev_b32_e32 v131, 21, v20
	v_cmp_eq_u32_e32 vcc, s55, v131
	v_lshrrev_b32_e32 v229, 8, v20
	v_and_b32_e32 v229, 0x1ffc, v229
	v_add_u32_e32 v229, s97, v229
	v_cndmask_b32_e32 v229, v231, v229, vcc
	ds_add_u32 v229, v176 offset:41984
	v_lshrrev_b32_e32 v131, 21, v19
	v_cmp_eq_u32_e32 vcc, s55, v131
	v_lshrrev_b32_e32 v229, 8, v19
	v_and_b32_e32 v229, 0x1ffc, v229
	v_add_u32_e32 v229, s97, v229
	v_cndmask_b32_e32 v229, v231, v229, vcc
	ds_add_u32 v229, v176 offset:41984
	v_lshrrev_b32_e32 v131, 21, v15
	v_cmp_eq_u32_e32 vcc, s55, v131
	v_lshrrev_b32_e32 v229, 8, v15
	v_and_b32_e32 v229, 0x1ffc, v229
	v_add_u32_e32 v229, s97, v229
	v_cndmask_b32_e32 v229, v231, v229, vcc
	ds_add_u32 v229, v176 offset:41984
	v_cndmask_b32_e64 v131, 0, 1, s[62:63]
	v_cmp_ne_u32_e64 s[38:39], 1, v131
	s_andn2_b64 vcc, exec, s[62:63]
	s_cbranch_vccnz .LBB0_607
; template <int SHIFT, int NBITS, bool FIRST>
; __device__ __forceinline__ void radix_pass(const unsigned (&uu)[128], int nreg, unsigned* hist, int lane, unsigned& prefix, int& need) {
;     ...
;     for (int g = 0; g < 8; ++g) {
;         if (g * 16 < nreg) {
; #pragma unroll
;             for (int r = g * 16; r < g * 16 + 16; ++r) {
;                 const unsigned u = uu[r];
;                 const bool match = FIRST ? true : ((u >> (SHIFT + NBITS)) == prefix);
;                 if (match) __hip_atomic_fetch_add(hist + ((u >> SHIFT) & (NBINS - 1)), 1u, __ATOMIC_RELAXED, __HIP_MEMORY_SCOPE_WORKGROUP);
;             }
;         }
;     }
.LBB0_574:
	v_lshrrev_b32_e32 v131, 21, v18
	v_cmp_eq_u32_e32 vcc, s55, v131
	v_lshrrev_b32_e32 v229, 8, v18
	v_and_b32_e32 v229, 0x1ffc, v229
	v_add_u32_e32 v229, s97, v229
	v_cndmask_b32_e32 v229, v231, v229, vcc
	ds_add_u32 v229, v176 offset:41984
	v_lshrrev_b32_e32 v131, 21, v17
	v_cmp_eq_u32_e32 vcc, s55, v131
	v_lshrrev_b32_e32 v229, 8, v17
	v_and_b32_e32 v229, 0x1ffc, v229
	v_add_u32_e32 v229, s97, v229
	v_cndmask_b32_e32 v229, v231, v229, vcc
	ds_add_u32 v229, v176 offset:41984
	v_lshrrev_b32_e32 v131, 21, v16
	v_cmp_eq_u32_e32 vcc, s55, v131
	v_lshrrev_b32_e32 v229, 8, v16
	v_and_b32_e32 v229, 0x1ffc, v229
	v_add_u32_e32 v229, s97, v229
	v_cndmask_b32_e32 v229, v231, v229, vcc
	ds_add_u32 v229, v176 offset:41984
	v_lshrrev_b32_e32 v131, 21, v14
	v_cmp_eq_u32_e32 vcc, s55, v131
	v_lshrrev_b32_e32 v229, 8, v14
	v_and_b32_e32 v229, 0x1ffc, v229
	v_add_u32_e32 v229, s97, v229
	v_cndmask_b32_e32 v229, v231, v229, vcc
	ds_add_u32 v229, v176 offset:41984
	v_lshrrev_b32_e32 v131, 21, v13
	v_cmp_eq_u32_e32 vcc, s55, v131
	v_lshrrev_b32_e32 v229, 8, v13
	v_and_b32_e32 v229, 0x1ffc, v229
	v_add_u32_e32 v229, s97, v229
	v_cndmask_b32_e32 v229, v231, v229, vcc
	ds_add_u32 v229, v176 offset:41984
	v_lshrrev_b32_e32 v131, 21, v12
	v_cmp_eq_u32_e32 vcc, s55, v131
	v_lshrrev_b32_e32 v229, 8, v12
	v_and_b32_e32 v229, 0x1ffc, v229
	v_add_u32_e32 v229, s97, v229
	v_cndmask_b32_e32 v229, v231, v229, vcc
	ds_add_u32 v229, v176 offset:41984
	v_lshrrev_b32_e32 v131, 21, v11
	v_cmp_eq_u32_e32 vcc, s55, v131
	v_lshrrev_b32_e32 v229, 8, v11
	v_and_b32_e32 v229, 0x1ffc, v229
	v_add_u32_e32 v229, s97, v229
	v_cndmask_b32_e32 v229, v231, v229, vcc
	ds_add_u32 v229, v176 offset:41984
	v_lshrrev_b32_e32 v131, 21, v10
	v_cmp_eq_u32_e32 vcc, s55, v131
	v_lshrrev_b32_e32 v229, 8, v10
	v_and_b32_e32 v229, 0x1ffc, v229
	v_add_u32_e32 v229, s97, v229
	v_cndmask_b32_e32 v229, v231, v229, vcc
	ds_add_u32 v229, v176 offset:41984
	v_lshrrev_b32_e32 v131, 21, v9
	v_cmp_eq_u32_e32 vcc, s55, v131
	v_lshrrev_b32_e32 v229, 8, v9
	v_and_b32_e32 v229, 0x1ffc, v229
	v_add_u32_e32 v229, s97, v229
	v_cndmask_b32_e32 v229, v231, v229, vcc
	ds_add_u32 v229, v176 offset:41984
	v_lshrrev_b32_e32 v131, 21, v8
	v_cmp_eq_u32_e32 vcc, s55, v131
	v_lshrrev_b32_e32 v229, 8, v8
	v_and_b32_e32 v229, 0x1ffc, v229
	v_add_u32_e32 v229, s97, v229
	v_cndmask_b32_e32 v229, v231, v229, vcc
	ds_add_u32 v229, v176 offset:41984
	v_lshrrev_b32_e32 v131, 21, v7
	v_cmp_eq_u32_e32 vcc, s55, v131
	v_lshrrev_b32_e32 v229, 8, v7
	v_and_b32_e32 v229, 0x1ffc, v229
	v_add_u32_e32 v229, s97, v229
	v_cndmask_b32_e32 v229, v231, v229, vcc
	ds_add_u32 v229, v176 offset:41984
	v_lshrrev_b32_e32 v131, 21, v6
	v_cmp_eq_u32_e32 vcc, s55, v131
	v_lshrrev_b32_e32 v229, 8, v6
	v_and_b32_e32 v229, 0x1ffc, v229
	v_add_u32_e32 v229, s97, v229
	v_cndmask_b32_e32 v229, v231, v229, vcc
	ds_add_u32 v229, v176 offset:41984
	v_lshrrev_b32_e32 v131, 21, v5
	v_cmp_eq_u32_e32 vcc, s55, v131
	v_lshrrev_b32_e32 v229, 8, v5
	v_and_b32_e32 v229, 0x1ffc, v229
	v_add_u32_e32 v229, s97, v229
	v_cndmask_b32_e32 v229, v231, v229, vcc
	ds_add_u32 v229, v176 offset:41984
	v_lshrrev_b32_e32 v131, 21, v4
	v_cmp_eq_u32_e32 vcc, s55, v131
	v_lshrrev_b32_e32 v229, 8, v4
	v_and_b32_e32 v229, 0x1ffc, v229
	v_add_u32_e32 v229, s97, v229
	v_cndmask_b32_e32 v229, v231, v229, vcc
	ds_add_u32 v229, v176 offset:41984
	v_lshrrev_b32_e32 v131, 21, v3
	v_cmp_eq_u32_e32 vcc, s55, v131
	v_lshrrev_b32_e32 v229, 8, v3
	v_and_b32_e32 v229, 0x1ffc, v229
	v_add_u32_e32 v229, s97, v229
	v_cndmask_b32_e32 v229, v231, v229, vcc
	ds_add_u32 v229, v176 offset:41984
	v_lshrrev_b32_e32 v131, 21, v2
	v_cmp_eq_u32_e32 vcc, s55, v131
	v_lshrrev_b32_e32 v229, 8, v2
	v_and_b32_e32 v229, 0x1ffc, v229
	v_add_u32_e32 v229, s97, v229
	v_cndmask_b32_e32 v229, v231, v229, vcc
	ds_add_u32 v229, v176 offset:41984
; #define WAVE_LDS_SYNC() do { __builtin_amdgcn_fence(__ATOMIC_RELEASE, "workgroup"); __builtin_amdgcn_wave_barrier(); __builtin_amdgcn_fence(__ATOMIC_ACQUIRE, "workgroup"); } while (0)
; template <int SHIFT, int NBITS, bool FIRST>
; __device__ __forceinline__ void radix_pass(const unsigned (&uu)[128], int nreg, unsigned* hist, int lane, unsigned& prefix, int& need) {
;     constexpr int NBINS = 1 << NBITS, BPL = NBINS / 64;
; #pragma unroll
;     for (int i = 0; i < NBINS / 256; ++i) *(u32x4*)(hist + (i * 64 + lane) * 4) = (u32x4){0u, 0u, 0u, 0u};
;     WAVE_LDS_SYNC();
; #pragma unroll
;     for (int g = 0; g < 8; ++g) {
;         if (g * 16 < nreg) {
; #pragma unroll
;             for (int r = g * 16; r < g * 16 + 16; ++r) {
;                 const unsigned u = uu[r];
;                 const bool match = FIRST ? true : ((u >> (SHIFT + NBITS)) == prefix);
;                 if (match) __hip_atomic_fetch_add(hist + ((u >> SHIFT) & (NBINS - 1)), 1u, __ATOMIC_RELAXED, __HIP_MEMORY_SCOPE_WORKGROUP);
;             }
;     ...
;     int T = 0;
;     {
;         const unsigned* hb = hist + (63 - lane) * BPL;
; #pragma unroll
;         for (int i = 0; i < BPL / 4; ++i) { const u32x4 c = *(const u32x4*)(hb + i * 4); T += (int)(c.x + c.y + c.z + c.w); }
;     }
;     const int P = wave_prefix_incl(T);
;     const unsigned long long m1 = __ballot(P >= need);
;     const int lo = __builtin_ctzll(m1);
;     const int above_blk = __builtin_amdgcn_readlane(P - T, lo);
;     const int base = (63 - lo) * BPL;
;     const int c2 = (lane < BPL) ? (int)hist[base + BPL - 1 - (lane < BPL ? lane : 0)] : 0;
;     const int P2 = wave_prefix_incl(c2);
;     const unsigned long long m2 = __ballot((lane < BPL) && (above_blk + P2 >= need));
;     const int j = __builtin_ctzll(m2);
;     const int above = above_blk + __builtin_amdgcn_readlane(P2 - c2, j);
;     prefix = (prefix << NBITS) | (unsigned)(base + BPL - 1 - j);
;     need -= above;
.LBB0_607:
	s_waitcnt lgkmcnt(0)
	ds_read_b128 v[132:135], v130 offset:50048
	ds_read_b128 v[136:139], v130 offset:50064
	ds_read_b128 v[140:143], v130 offset:50080
	ds_read_b128 v[144:147], v130 offset:50096
	s_add_i32 s59, s59, s61
	s_sub_i32 s59, 0x100, s59
	s_waitcnt lgkmcnt(3)
	v_add_u32_e32 v131, v133, v132
	v_add3_u32 v131, v131, v134, v135
	s_waitcnt lgkmcnt(2)
	v_add3_u32 v131, v131, v137, v136
	v_add3_u32 v131, v131, v138, v139
	ds_read_b128 v[132:135], v130 offset:50112
	ds_read_b128 v[136:139], v130 offset:50128
	s_waitcnt lgkmcnt(3)
	v_add3_u32 v131, v131, v141, v140
	v_add3_u32 v131, v131, v142, v143
	s_waitcnt lgkmcnt(2)
	v_add3_u32 v131, v131, v145, v144
	v_add3_u32 v131, v131, v146, v147
	ds_read_b128 v[140:143], v130 offset:50144
	s_waitcnt lgkmcnt(2)
	v_add3_u32 v131, v131, v133, v132
	v_add3_u32 v134, v131, v134, v135
	ds_read_b128 v[130:133], v130 offset:50160
	s_waitcnt lgkmcnt(2)
	v_add3_u32 v134, v134, v137, v136
	v_add3_u32 v134, v134, v138, v139
	s_waitcnt lgkmcnt(1)
	v_add3_u32 v134, v134, v141, v140
	v_add3_u32 v134, v134, v142, v143
	s_waitcnt lgkmcnt(0)
	v_add3_u32 v130, v134, v131, v130
	v_add3_u32 v131, v130, v132, v133
	v_mov_b32_e32 v130, 0
	s_nop 0
	v_add_u32_dpp v132, v131, v131 row_shr:1 row_mask:0xf bank_mask:0xf bound_ctrl:1
	s_nop 1
	v_add_u32_dpp v132, v132, v132 row_shr:2 row_mask:0xf bank_mask:0xf bound_ctrl:1
	s_nop 1
	v_add_u32_dpp v132, v132, v132 row_shr:4 row_mask:0xf bank_mask:0xf bound_ctrl:1
	s_nop 1
	v_add_u32_dpp v132, v132, v132 row_shr:8 row_mask:0xf bank_mask:0xf bound_ctrl:1
	s_nop 1
	v_add_u32_dpp v132, v132, v132 row_bcast:15 row_mask:0xa bank_mask:0xf
	s_nop 1
	v_add_u32_dpp v132, v132, v132 row_bcast:31 row_mask:0xc bank_mask:0xf
	v_cmp_le_i32_e32 vcc, s59, v132
	s_ff1_i32_b64 s4, vcc
	v_sub_u32_e32 v131, v132, v131
	s_nop 0
	v_readlane_b32 s61, v131, s4
	s_lshl_b32 s4, s4, 5
	s_xor_b32 s41, s4, 0x7e0
	s_and_saveexec_b64 s[42:43], s[22:23]
	v_sub_u32_e32 v130, s41, v1
	v_lshl_add_u32 v130, v130, 2, s97
	ds_read_b32 v130, v130 offset:42108
	s_or_b64 exec, exec, s[42:43]
	s_waitcnt lgkmcnt(0)
	v_add_u32_dpp v131, v130, v130 row_shr:1 row_mask:0xf bank_mask:0xf bound_ctrl:1
	s_mov_b32 s42, s40
	s_mov_b32 s43, s40
	v_add_u32_dpp v131, v131, v131 row_shr:2 row_mask:0xf bank_mask:0xf bound_ctrl:1
	s_nop 1
	v_add_u32_dpp v131, v131, v131 row_shr:4 row_mask:0xf bank_mask:0xf bound_ctrl:1
	s_nop 1
	v_add_u32_dpp v131, v131, v131 row_shr:8 row_mask:0xf bank_mask:0xf bound_ctrl:1
	s_nop 1
	v_add_u32_dpp v131, v131, v131 row_bcast:15 row_mask:0xa bank_mask:0xf
	s_nop 1
	v_add_u32_dpp v131, v131, v131 row_bcast:31 row_mask:0xc bank_mask:0xf
	v_add_u32_e32 v132, s61, v131
	v_cmp_le_i32_e32 vcc, s59, v132
	s_and_b64 s[4:5], s[22:23], vcc
	v_cndmask_b32_e64 v132, 0, 1, s[4:5]
	v_cmp_ne_u32_e32 vcc, 0, v132
	s_ff1_i32_b64 s4, vcc
	v_sub_u32_e32 v130, v131, v130
	s_or_b32 s22, s41, 31
	v_readlane_b32 s62, v130, s4
	s_mov_b32 s41, s40
	v_mov_b64_e32 v[132:133], s[42:43]
	s_lshl_b32 s5, s55, 11
	s_sub_i32 s4, s22, s4
	v_mov_b64_e32 v[130:131], s[40:41]
	s_or_b32 s55, s4, s5
	ds_write_b128 v129, v[130:133] offset:41984
	ds_write_b128 v129, v[130:133] offset:43008
	ds_write_b128 v129, v[130:133] offset:44032
	ds_write_b128 v129, v[130:133] offset:45056
	v_lshrrev_b32_e32 v129, 10, v0
	v_cmp_eq_u32_e32 vcc, s55, v129
	s_waitcnt lgkmcnt(0)
	s_and_saveexec_b64 s[22:23], vcc
	v_and_b32_e32 v129, 0x3ff, v0
	v_lshl_add_u32 v129, v129, 2, s97
	ds_add_u32 v129, v176 offset:41984
	s_or_b64 exec, exec, s[22:23]
	v_lshrrev_b32_e32 v129, 10, v128
	v_cmp_eq_u32_e32 vcc, s55, v129
	v_and_b32_e32 v229, 0x3ff, v128
	v_lshl_add_u32 v229, v229, 2, s97
	v_cndmask_b32_e32 v229, v231, v229, vcc
	ds_add_u32 v229, v176 offset:41984
	v_lshrrev_b32_e32 v129, 10, v127
	v_cmp_eq_u32_e32 vcc, s55, v129
	v_and_b32_e32 v229, 0x3ff, v127
	v_lshl_add_u32 v229, v229, 2, s97
	v_cndmask_b32_e32 v229, v231, v229, vcc
	ds_add_u32 v229, v176 offset:41984
	v_lshrrev_b32_e32 v129, 10, v126
	v_cmp_eq_u32_e32 vcc, s55, v129
	v_and_b32_e32 v229, 0x3ff, v126
	v_lshl_add_u32 v229, v229, 2, s97
	v_cndmask_b32_e32 v229, v231, v229, vcc
	ds_add_u32 v229, v176 offset:41984
	v_lshrrev_b32_e32 v129, 10, v125
	v_cmp_eq_u32_e32 vcc, s55, v129
	v_and_b32_e32 v229, 0x3ff, v125
	v_lshl_add_u32 v229, v229, 2, s97
	v_cndmask_b32_e32 v229, v231, v229, vcc
	ds_add_u32 v229, v176 offset:41984
	v_lshrrev_b32_e32 v129, 10, v124
	v_cmp_eq_u32_e32 vcc, s55, v129
	v_and_b32_e32 v229, 0x3ff, v124
	v_lshl_add_u32 v229, v229, 2, s97
	v_cndmask_b32_e32 v229, v231, v229, vcc
	ds_add_u32 v229, v176 offset:41984
	v_lshrrev_b32_e32 v129, 10, v123
	v_cmp_eq_u32_e32 vcc, s55, v129
	v_and_b32_e32 v229, 0x3ff, v123
	v_lshl_add_u32 v229, v229, 2, s97
	v_cndmask_b32_e32 v229, v231, v229, vcc
	ds_add_u32 v229, v176 offset:41984
	v_lshrrev_b32_e32 v129, 10, v122
	v_cmp_eq_u32_e32 vcc, s55, v129
	v_and_b32_e32 v229, 0x3ff, v122
	v_lshl_add_u32 v229, v229, 2, s97
	v_cndmask_b32_e32 v229, v231, v229, vcc
	ds_add_u32 v229, v176 offset:41984
	v_lshrrev_b32_e32 v129, 10, v121
	v_cmp_eq_u32_e32 vcc, s55, v129
	v_and_b32_e32 v229, 0x3ff, v121
	v_lshl_add_u32 v229, v229, 2, s97
	v_cndmask_b32_e32 v229, v231, v229, vcc
	ds_add_u32 v229, v176 offset:41984
	v_lshrrev_b32_e32 v129, 10, v120
	v_cmp_eq_u32_e32 vcc, s55, v129
	v_and_b32_e32 v229, 0x3ff, v120
	v_lshl_add_u32 v229, v229, 2, s97
	v_cndmask_b32_e32 v229, v231, v229, vcc
	ds_add_u32 v229, v176 offset:41984
	v_lshrrev_b32_e32 v129, 10, v119
	v_cmp_eq_u32_e32 vcc, s55, v129
	v_and_b32_e32 v229, 0x3ff, v119
	v_lshl_add_u32 v229, v229, 2, s97
	v_cndmask_b32_e32 v229, v231, v229, vcc
	ds_add_u32 v229, v176 offset:41984
	v_lshrrev_b32_e32 v129, 10, v118
	v_cmp_eq_u32_e32 vcc, s55, v129
	v_and_b32_e32 v229, 0x3ff, v118
	v_lshl_add_u32 v229, v229, 2, s97
	v_cndmask_b32_e32 v229, v231, v229, vcc
	ds_add_u32 v229, v176 offset:41984
	v_lshrrev_b32_e32 v129, 10, v117
	v_cmp_eq_u32_e32 vcc, s55, v129
	v_and_b32_e32 v229, 0x3ff, v117
	v_lshl_add_u32 v229, v229, 2, s97
	v_cndmask_b32_e32 v229, v231, v229, vcc
	ds_add_u32 v229, v176 offset:41984
	v_lshrrev_b32_e32 v129, 10, v116
	v_cmp_eq_u32_e32 vcc, s55, v129
	v_and_b32_e32 v229, 0x3ff, v116
	v_lshl_add_u32 v229, v229, 2, s97
	v_cndmask_b32_e32 v229, v231, v229, vcc
	ds_add_u32 v229, v176 offset:41984
	v_lshrrev_b32_e32 v129, 10, v115
	v_cmp_eq_u32_e32 vcc, s55, v129
	v_and_b32_e32 v229, 0x3ff, v115
	v_lshl_add_u32 v229, v229, 2, s97
	v_cndmask_b32_e32 v229, v231, v229, vcc
	ds_add_u32 v229, v176 offset:41984
	v_lshrrev_b32_e32 v129, 10, v114
	v_cmp_eq_u32_e32 vcc, s55, v129
	s_and_saveexec_b64 s[22:23], vcc
	s_cbranch_execnz .LBB0_647
	s_or_b64 exec, exec, s[22:23]
	s_and_b64 vcc, exec, s[24:25]
	s_cbranch_vccz .LBB0_648

; template <int SHIFT, int NBITS, bool FIRST>
; __device__ __forceinline__ void radix_pass(const unsigned (&uu)[128], int nreg, unsigned* hist, int lane, unsigned& prefix, int& need) {
;     ...
;     for (int g = 0; g < 8; ++g) {
;         if (g * 16 < nreg) {
; #pragma unroll
;             for (int r = g * 16; r < g * 16 + 16; ++r) {
;                 const unsigned u = uu[r];
;                 const bool match = FIRST ? true : ((u >> (SHIFT + NBITS)) == prefix);
;                 if (match) __hip_atomic_fetch_add(hist + ((u >> SHIFT) & (NBINS - 1)), 1u, __ATOMIC_RELAXED, __HIP_MEMORY_SCOPE_WORKGROUP);
;             }
;         }
;     }
.LBB0_648:
	v_lshrrev_b32_e32 v129, 10, v113
	v_cmp_eq_u32_e32 vcc, s55, v129
	v_and_b32_e32 v229, 0x3ff, v113
	v_lshl_add_u32 v229, v229, 2, s97
	v_cndmask_b32_e32 v229, v231, v229, vcc
	ds_add_u32 v229, v176 offset:41984
	v_lshrrev_b32_e32 v129, 10, v112
	v_cmp_eq_u32_e32 vcc, s55, v129
	v_and_b32_e32 v229, 0x3ff, v112
	v_lshl_add_u32 v229, v229, 2, s97
	v_cndmask_b32_e32 v229, v231, v229, vcc
	ds_add_u32 v229, v176 offset:41984
	v_lshrrev_b32_e32 v129, 10, v111
	v_cmp_eq_u32_e32 vcc, s55, v129
	v_and_b32_e32 v229, 0x3ff, v111
	v_lshl_add_u32 v229, v229, 2, s97
	v_cndmask_b32_e32 v229, v231, v229, vcc
	ds_add_u32 v229, v176 offset:41984
	v_lshrrev_b32_e32 v129, 10, v110
	v_cmp_eq_u32_e32 vcc, s55, v129
	v_and_b32_e32 v229, 0x3ff, v110
	v_lshl_add_u32 v229, v229, 2, s97
	v_cndmask_b32_e32 v229, v231, v229, vcc
	ds_add_u32 v229, v176 offset:41984
	v_lshrrev_b32_e32 v129, 10, v109
	v_cmp_eq_u32_e32 vcc, s55, v129
	v_and_b32_e32 v229, 0x3ff, v109
	v_lshl_add_u32 v229, v229, 2, s97
	v_cndmask_b32_e32 v229, v231, v229, vcc
	ds_add_u32 v229, v176 offset:41984
	v_lshrrev_b32_e32 v129, 10, v108
	v_cmp_eq_u32_e32 vcc, s55, v129
	v_and_b32_e32 v229, 0x3ff, v108
	v_lshl_add_u32 v229, v229, 2, s97
	v_cndmask_b32_e32 v229, v231, v229, vcc
	ds_add_u32 v229, v176 offset:41984
	v_lshrrev_b32_e32 v129, 10, v107
	v_cmp_eq_u32_e32 vcc, s55, v129
	v_and_b32_e32 v229, 0x3ff, v107
	v_lshl_add_u32 v229, v229, 2, s97
	v_cndmask_b32_e32 v229, v231, v229, vcc
	ds_add_u32 v229, v176 offset:41984
	v_lshrrev_b32_e32 v129, 10, v106
	v_cmp_eq_u32_e32 vcc, s55, v129
	v_and_b32_e32 v229, 0x3ff, v106
	v_lshl_add_u32 v229, v229, 2, s97
	v_cndmask_b32_e32 v229, v231, v229, vcc
	ds_add_u32 v229, v176 offset:41984
	v_lshrrev_b32_e32 v129, 10, v105
	v_cmp_eq_u32_e32 vcc, s55, v129
	v_and_b32_e32 v229, 0x3ff, v105
	v_lshl_add_u32 v229, v229, 2, s97
	v_cndmask_b32_e32 v229, v231, v229, vcc
	ds_add_u32 v229, v176 offset:41984
	v_lshrrev_b32_e32 v129, 10, v104
	v_cmp_eq_u32_e32 vcc, s55, v129
	v_and_b32_e32 v229, 0x3ff, v104
	v_lshl_add_u32 v229, v229, 2, s97
	v_cndmask_b32_e32 v229, v231, v229, vcc
	ds_add_u32 v229, v176 offset:41984
	v_lshrrev_b32_e32 v129, 10, v103
	v_cmp_eq_u32_e32 vcc, s55, v129
	v_and_b32_e32 v229, 0x3ff, v103
	v_lshl_add_u32 v229, v229, 2, s97
	v_cndmask_b32_e32 v229, v231, v229, vcc
	ds_add_u32 v229, v176 offset:41984
	v_lshrrev_b32_e32 v129, 10, v102
	v_cmp_eq_u32_e32 vcc, s55, v129
	v_and_b32_e32 v229, 0x3ff, v102
	v_lshl_add_u32 v229, v229, 2, s97
	v_cndmask_b32_e32 v229, v231, v229, vcc
	ds_add_u32 v229, v176 offset:41984
	v_lshrrev_b32_e32 v129, 10, v101
	v_cmp_eq_u32_e32 vcc, s55, v129
	v_and_b32_e32 v229, 0x3ff, v101
	v_lshl_add_u32 v229, v229, 2, s97
	v_cndmask_b32_e32 v229, v231, v229, vcc
	ds_add_u32 v229, v176 offset:41984
	v_lshrrev_b32_e32 v129, 10, v100
	v_cmp_eq_u32_e32 vcc, s55, v129
	v_and_b32_e32 v229, 0x3ff, v100
	v_lshl_add_u32 v229, v229, 2, s97
	v_cndmask_b32_e32 v229, v231, v229, vcc
	ds_add_u32 v229, v176 offset:41984
	v_lshrrev_b32_e32 v129, 10, v99
	v_cmp_eq_u32_e32 vcc, s55, v129
	v_and_b32_e32 v229, 0x3ff, v99
	v_lshl_add_u32 v229, v229, 2, s97
	v_cndmask_b32_e32 v229, v231, v229, vcc
	ds_add_u32 v229, v176 offset:41984
	v_lshrrev_b32_e32 v129, 10, v97
	v_cmp_eq_u32_e32 vcc, s55, v129
	v_and_b32_e32 v229, 0x3ff, v97
	v_lshl_add_u32 v229, v229, 2, s97
	v_cndmask_b32_e32 v229, v231, v229, vcc
	ds_add_u32 v229, v176 offset:41984
	s_and_b64 vcc, exec, s[26:27]
	s_cbranch_vccnz .LBB0_642
.LBB0_681:
	v_lshrrev_b32_e32 v129, 10, v98
	v_cmp_eq_u32_e32 vcc, s55, v129
	v_and_b32_e32 v229, 0x3ff, v98
	v_lshl_add_u32 v229, v229, 2, s97
	v_cndmask_b32_e32 v229, v231, v229, vcc
	ds_add_u32 v229, v176 offset:41984
	v_lshrrev_b32_e32 v129, 10, v96
	v_cmp_eq_u32_e32 vcc, s55, v129
	v_and_b32_e32 v229, 0x3ff, v96
	v_lshl_add_u32 v229, v229, 2, s97
	v_cndmask_b32_e32 v229, v231, v229, vcc
	ds_add_u32 v229, v176 offset:41984
	v_lshrrev_b32_e32 v129, 10, v95
	v_cmp_eq_u32_e32 vcc, s55, v129
	v_and_b32_e32 v229, 0x3ff, v95
	v_lshl_add_u32 v229, v229, 2, s97
	v_cndmask_b32_e32 v229, v231, v229, vcc
	ds_add_u32 v229, v176 offset:41984
	v_lshrrev_b32_e32 v129, 10, v94
	v_cmp_eq_u32_e32 vcc, s55, v129
	v_and_b32_e32 v229, 0x3ff, v94
	v_lshl_add_u32 v229, v229, 2, s97
	v_cndmask_b32_e32 v229, v231, v229, vcc
	ds_add_u32 v229, v176 offset:41984
	v_lshrrev_b32_e32 v129, 10, v93
	v_cmp_eq_u32_e32 vcc, s55, v129
	v_and_b32_e32 v229, 0x3ff, v93
	v_lshl_add_u32 v229, v229, 2, s97
	v_cndmask_b32_e32 v229, v231, v229, vcc
	ds_add_u32 v229, v176 offset:41984
	v_lshrrev_b32_e32 v129, 10, v92
	v_cmp_eq_u32_e32 vcc, s55, v129
	v_and_b32_e32 v229, 0x3ff, v92
	v_lshl_add_u32 v229, v229, 2, s97
	v_cndmask_b32_e32 v229, v231, v229, vcc
	ds_add_u32 v229, v176 offset:41984
	v_lshrrev_b32_e32 v129, 10, v91
	v_cmp_eq_u32_e32 vcc, s55, v129
	v_and_b32_e32 v229, 0x3ff, v91
	v_lshl_add_u32 v229, v229, 2, s97
	v_cndmask_b32_e32 v229, v231, v229, vcc
	ds_add_u32 v229, v176 offset:41984
	v_lshrrev_b32_e32 v129, 10, v90
	v_cmp_eq_u32_e32 vcc, s55, v129
	v_and_b32_e32 v229, 0x3ff, v90
	v_lshl_add_u32 v229, v229, 2, s97
	v_cndmask_b32_e32 v229, v231, v229, vcc
	ds_add_u32 v229, v176 offset:41984
	v_lshrrev_b32_e32 v129, 10, v89
	v_cmp_eq_u32_e32 vcc, s55, v129
	v_and_b32_e32 v229, 0x3ff, v89
	v_lshl_add_u32 v229, v229, 2, s97
	v_cndmask_b32_e32 v229, v231, v229, vcc
	ds_add_u32 v229, v176 offset:41984
	v_lshrrev_b32_e32 v129, 10, v88
	v_cmp_eq_u32_e32 vcc, s55, v129
	v_and_b32_e32 v229, 0x3ff, v88
	v_lshl_add_u32 v229, v229, 2, s97
	v_cndmask_b32_e32 v229, v231, v229, vcc
	ds_add_u32 v229, v176 offset:41984
	v_lshrrev_b32_e32 v129, 10, v87
	v_cmp_eq_u32_e32 vcc, s55, v129
	v_and_b32_e32 v229, 0x3ff, v87
	v_lshl_add_u32 v229, v229, 2, s97
	v_cndmask_b32_e32 v229, v231, v229, vcc
	ds_add_u32 v229, v176 offset:41984
	v_lshrrev_b32_e32 v129, 10, v86
	v_cmp_eq_u32_e32 vcc, s55, v129
	v_and_b32_e32 v229, 0x3ff, v86
	v_lshl_add_u32 v229, v229, 2, s97
	v_cndmask_b32_e32 v229, v231, v229, vcc
	ds_add_u32 v229, v176 offset:41984
	v_lshrrev_b32_e32 v129, 10, v85
	v_cmp_eq_u32_e32 vcc, s55, v129
	v_and_b32_e32 v229, 0x3ff, v85
	v_lshl_add_u32 v229, v229, 2, s97
	v_cndmask_b32_e32 v229, v231, v229, vcc
	ds_add_u32 v229, v176 offset:41984
	v_lshrrev_b32_e32 v129, 10, v84
	v_cmp_eq_u32_e32 vcc, s55, v129
	v_and_b32_e32 v229, 0x3ff, v84
	v_lshl_add_u32 v229, v229, 2, s97
	v_cndmask_b32_e32 v229, v231, v229, vcc
	ds_add_u32 v229, v176 offset:41984
	v_lshrrev_b32_e32 v129, 10, v83
	v_cmp_eq_u32_e32 vcc, s55, v129
	v_and_b32_e32 v229, 0x3ff, v83
	v_lshl_add_u32 v229, v229, 2, s97
	v_cndmask_b32_e32 v229, v231, v229, vcc
	ds_add_u32 v229, v176 offset:41984
	v_lshrrev_b32_e32 v129, 10, v79
	v_cmp_eq_u32_e32 vcc, s55, v129
	v_and_b32_e32 v229, 0x3ff, v79
	v_lshl_add_u32 v229, v229, 2, s97
	v_cndmask_b32_e32 v229, v231, v229, vcc
	ds_add_u32 v229, v176 offset:41984
	s_and_b64 vcc, exec, s[28:29]
	s_cbranch_vccnz .LBB0_643
; template <int SHIFT, int NBITS, bool FIRST>
; __device__ __forceinline__ void radix_pass(const unsigned (&uu)[128], int nreg, unsigned* hist, int lane, unsigned& prefix, int& need) {
;     ...
;     for (int g = 0; g < 8; ++g) {
;         if (g * 16 < nreg) {
; #pragma unroll
;             for (int r = g * 16; r < g * 16 + 16; ++r) {
;                 const unsigned u = uu[r];
;                 const bool match = FIRST ? true : ((u >> (SHIFT + NBITS)) == prefix);
;                 if (match) __hip_atomic_fetch_add(hist + ((u >> SHIFT) & (NBINS - 1)), 1u, __ATOMIC_RELAXED, __HIP_MEMORY_SCOPE_WORKGROUP);
;             }
;         }
;     }
.LBB0_714:
	v_lshrrev_b32_e32 v129, 10, v82
	v_cmp_eq_u32_e32 vcc, s55, v129
	v_and_b32_e32 v229, 0x3ff, v82
	v_lshl_add_u32 v229, v229, 2, s97
	v_cndmask_b32_e32 v229, v231, v229, vcc
	ds_add_u32 v229, v176 offset:41984
	v_lshrrev_b32_e32 v129, 10, v81
	v_cmp_eq_u32_e32 vcc, s55, v129
	v_and_b32_e32 v229, 0x3ff, v81
	v_lshl_add_u32 v229, v229, 2, s97
	v_cndmask_b32_e32 v229, v231, v229, vcc
	ds_add_u32 v229, v176 offset:41984
	v_lshrrev_b32_e32 v129, 10, v80
	v_cmp_eq_u32_e32 vcc, s55, v129
	v_and_b32_e32 v229, 0x3ff, v80
	v_lshl_add_u32 v229, v229, 2, s97
	v_cndmask_b32_e32 v229, v231, v229, vcc
	ds_add_u32 v229, v176 offset:41984
	v_lshrrev_b32_e32 v129, 10, v78
	v_cmp_eq_u32_e32 vcc, s55, v129
	v_and_b32_e32 v229, 0x3ff, v78
	v_lshl_add_u32 v229, v229, 2, s97
	v_cndmask_b32_e32 v229, v231, v229, vcc
	ds_add_u32 v229, v176 offset:41984
	v_lshrrev_b32_e32 v129, 10, v77
	v_cmp_eq_u32_e32 vcc, s55, v129
	v_and_b32_e32 v229, 0x3ff, v77
	v_lshl_add_u32 v229, v229, 2, s97
	v_cndmask_b32_e32 v229, v231, v229, vcc
	ds_add_u32 v229, v176 offset:41984
	v_lshrrev_b32_e32 v129, 10, v76
	v_cmp_eq_u32_e32 vcc, s55, v129
	v_and_b32_e32 v229, 0x3ff, v76
	v_lshl_add_u32 v229, v229, 2, s97
	v_cndmask_b32_e32 v229, v231, v229, vcc
	ds_add_u32 v229, v176 offset:41984
	v_lshrrev_b32_e32 v129, 10, v75
	v_cmp_eq_u32_e32 vcc, s55, v129
	v_and_b32_e32 v229, 0x3ff, v75
	v_lshl_add_u32 v229, v229, 2, s97
	v_cndmask_b32_e32 v229, v231, v229, vcc
	ds_add_u32 v229, v176 offset:41984
	v_lshrrev_b32_e32 v129, 10, v74
	v_cmp_eq_u32_e32 vcc, s55, v129
	v_and_b32_e32 v229, 0x3ff, v74
	v_lshl_add_u32 v229, v229, 2, s97
	v_cndmask_b32_e32 v229, v231, v229, vcc
	ds_add_u32 v229, v176 offset:41984
	v_lshrrev_b32_e32 v129, 10, v73
	v_cmp_eq_u32_e32 vcc, s55, v129
	v_and_b32_e32 v229, 0x3ff, v73
	v_lshl_add_u32 v229, v229, 2, s97
	v_cndmask_b32_e32 v229, v231, v229, vcc
	ds_add_u32 v229, v176 offset:41984
	v_lshrrev_b32_e32 v129, 10, v72
	v_cmp_eq_u32_e32 vcc, s55, v129
	v_and_b32_e32 v229, 0x3ff, v72
	v_lshl_add_u32 v229, v229, 2, s97
	v_cndmask_b32_e32 v229, v231, v229, vcc
	ds_add_u32 v229, v176 offset:41984
	v_lshrrev_b32_e32 v129, 10, v71
	v_cmp_eq_u32_e32 vcc, s55, v129
	v_and_b32_e32 v229, 0x3ff, v71
	v_lshl_add_u32 v229, v229, 2, s97
	v_cndmask_b32_e32 v229, v231, v229, vcc
	ds_add_u32 v229, v176 offset:41984
	v_lshrrev_b32_e32 v129, 10, v70
	v_cmp_eq_u32_e32 vcc, s55, v129
	v_and_b32_e32 v229, 0x3ff, v70
	v_lshl_add_u32 v229, v229, 2, s97
	v_cndmask_b32_e32 v229, v231, v229, vcc
	ds_add_u32 v229, v176 offset:41984
	v_lshrrev_b32_e32 v129, 10, v69
	v_cmp_eq_u32_e32 vcc, s55, v129
	v_and_b32_e32 v229, 0x3ff, v69
	v_lshl_add_u32 v229, v229, 2, s97
	v_cndmask_b32_e32 v229, v231, v229, vcc
	ds_add_u32 v229, v176 offset:41984
	v_lshrrev_b32_e32 v129, 10, v68
	v_cmp_eq_u32_e32 vcc, s55, v129
	v_and_b32_e32 v229, 0x3ff, v68
	v_lshl_add_u32 v229, v229, 2, s97
	v_cndmask_b32_e32 v229, v231, v229, vcc
	ds_add_u32 v229, v176 offset:41984
	v_lshrrev_b32_e32 v129, 10, v67
	v_cmp_eq_u32_e32 vcc, s55, v129
	v_and_b32_e32 v229, 0x3ff, v67
	v_lshl_add_u32 v229, v229, 2, s97
	v_cndmask_b32_e32 v229, v231, v229, vcc
	ds_add_u32 v229, v176 offset:41984
	v_lshrrev_b32_e32 v129, 10, v65
	v_cmp_eq_u32_e32 vcc, s55, v129
	v_and_b32_e32 v229, 0x3ff, v65
	v_lshl_add_u32 v229, v229, 2, s97
	v_cndmask_b32_e32 v229, v231, v229, vcc
	ds_add_u32 v229, v176 offset:41984
	s_and_b64 vcc, exec, s[30:31]
	s_cbranch_vccnz .LBB0_644
.LBB0_747:
	v_lshrrev_b32_e32 v129, 10, v66
	v_cmp_eq_u32_e32 vcc, s55, v129
	v_and_b32_e32 v229, 0x3ff, v66
	v_lshl_add_u32 v229, v229, 2, s97
	v_cndmask_b32_e32 v229, v231, v229, vcc
	ds_add_u32 v229, v176 offset:41984
	v_lshrrev_b32_e32 v129, 10, v64
	v_cmp_eq_u32_e32 vcc, s55, v129
	v_and_b32_e32 v229, 0x3ff, v64
	v_lshl_add_u32 v229, v229, 2, s97
	v_cndmask_b32_e32 v229, v231, v229, vcc
	ds_add_u32 v229, v176 offset:41984
	v_lshrrev_b32_e32 v129, 10, v63
	v_cmp_eq_u32_e32 vcc, s55, v129
	v_and_b32_e32 v229, 0x3ff, v63
	v_lshl_add_u32 v229, v229, 2, s97
	v_cndmask_b32_e32 v229, v231, v229, vcc
	ds_add_u32 v229, v176 offset:41984
	v_lshrrev_b32_e32 v129, 10, v62
	v_cmp_eq_u32_e32 vcc, s55, v129
	v_and_b32_e32 v229, 0x3ff, v62
	v_lshl_add_u32 v229, v229, 2, s97
	v_cndmask_b32_e32 v229, v231, v229, vcc
	ds_add_u32 v229, v176 offset:41984
	v_lshrrev_b32_e32 v129, 10, v61
	v_cmp_eq_u32_e32 vcc, s55, v129
	v_and_b32_e32 v229, 0x3ff, v61
	v_lshl_add_u32 v229, v229, 2, s97
	v_cndmask_b32_e32 v229, v231, v229, vcc
	ds_add_u32 v229, v176 offset:41984
	v_lshrrev_b32_e32 v129, 10, v60
	v_cmp_eq_u32_e32 vcc, s55, v129
	v_and_b32_e32 v229, 0x3ff, v60
	v_lshl_add_u32 v229, v229, 2, s97
	v_cndmask_b32_e32 v229, v231, v229, vcc
	ds_add_u32 v229, v176 offset:41984
	v_lshrrev_b32_e32 v129, 10, v59
	v_cmp_eq_u32_e32 vcc, s55, v129
	v_and_b32_e32 v229, 0x3ff, v59
	v_lshl_add_u32 v229, v229, 2, s97
	v_cndmask_b32_e32 v229, v231, v229, vcc
	ds_add_u32 v229, v176 offset:41984
	v_lshrrev_b32_e32 v129, 10, v58
	v_cmp_eq_u32_e32 vcc, s55, v129
	v_and_b32_e32 v229, 0x3ff, v58
	v_lshl_add_u32 v229, v229, 2, s97
	v_cndmask_b32_e32 v229, v231, v229, vcc
	ds_add_u32 v229, v176 offset:41984
	v_lshrrev_b32_e32 v129, 10, v57
	v_cmp_eq_u32_e32 vcc, s55, v129
	v_and_b32_e32 v229, 0x3ff, v57
	v_lshl_add_u32 v229, v229, 2, s97
	v_cndmask_b32_e32 v229, v231, v229, vcc
	ds_add_u32 v229, v176 offset:41984
	v_lshrrev_b32_e32 v129, 10, v56
	v_cmp_eq_u32_e32 vcc, s55, v129
	v_and_b32_e32 v229, 0x3ff, v56
	v_lshl_add_u32 v229, v229, 2, s97
	v_cndmask_b32_e32 v229, v231, v229, vcc
	ds_add_u32 v229, v176 offset:41984
	v_lshrrev_b32_e32 v129, 10, v55
	v_cmp_eq_u32_e32 vcc, s55, v129
	v_and_b32_e32 v229, 0x3ff, v55
	v_lshl_add_u32 v229, v229, 2, s97
	v_cndmask_b32_e32 v229, v231, v229, vcc
	ds_add_u32 v229, v176 offset:41984
	v_lshrrev_b32_e32 v129, 10, v54
	v_cmp_eq_u32_e32 vcc, s55, v129
	v_and_b32_e32 v229, 0x3ff, v54
	v_lshl_add_u32 v229, v229, 2, s97
	v_cndmask_b32_e32 v229, v231, v229, vcc
	ds_add_u32 v229, v176 offset:41984
	v_lshrrev_b32_e32 v129, 10, v53
	v_cmp_eq_u32_e32 vcc, s55, v129
	v_and_b32_e32 v229, 0x3ff, v53
	v_lshl_add_u32 v229, v229, 2, s97
	v_cndmask_b32_e32 v229, v231, v229, vcc
	ds_add_u32 v229, v176 offset:41984
	v_lshrrev_b32_e32 v129, 10, v52
	v_cmp_eq_u32_e32 vcc, s55, v129
	v_and_b32_e32 v229, 0x3ff, v52
	v_lshl_add_u32 v229, v229, 2, s97
	v_cndmask_b32_e32 v229, v231, v229, vcc
	ds_add_u32 v229, v176 offset:41984
	v_lshrrev_b32_e32 v129, 10, v51
	v_cmp_eq_u32_e32 vcc, s55, v129
	v_and_b32_e32 v229, 0x3ff, v51
	v_lshl_add_u32 v229, v229, 2, s97
	v_cndmask_b32_e32 v229, v231, v229, vcc
	ds_add_u32 v229, v176 offset:41984
	v_lshrrev_b32_e32 v129, 10, v47
	v_cmp_eq_u32_e32 vcc, s55, v129
	v_and_b32_e32 v229, 0x3ff, v47
	v_lshl_add_u32 v229, v229, 2, s97
	v_cndmask_b32_e32 v229, v231, v229, vcc
	ds_add_u32 v229, v176 offset:41984
	s_and_b64 vcc, exec, s[34:35]
	s_cbranch_vccnz .LBB0_645
; template <int SHIFT, int NBITS, bool FIRST>
; __device__ __forceinline__ void radix_pass(const unsigned (&uu)[128], int nreg, unsigned* hist, int lane, unsigned& prefix, int& need) {
;     ...
;     for (int g = 0; g < 8; ++g) {
;         if (g * 16 < nreg) {
; #pragma unroll
;             for (int r = g * 16; r < g * 16 + 16; ++r) {
;                 const unsigned u = uu[r];
;                 const bool match = FIRST ? true : ((u >> (SHIFT + NBITS)) == prefix);
;                 if (match) __hip_atomic_fetch_add(hist + ((u >> SHIFT) & (NBINS - 1)), 1u, __ATOMIC_RELAXED, __HIP_MEMORY_SCOPE_WORKGROUP);
;             }
;         }
;     }
.LBB0_780:
	v_lshrrev_b32_e32 v129, 10, v50
	v_cmp_eq_u32_e32 vcc, s55, v129
	v_and_b32_e32 v229, 0x3ff, v50
	v_lshl_add_u32 v229, v229, 2, s97
	v_cndmask_b32_e32 v229, v231, v229, vcc
	ds_add_u32 v229, v176 offset:41984
	v_lshrrev_b32_e32 v129, 10, v49
	v_cmp_eq_u32_e32 vcc, s55, v129
	v_and_b32_e32 v229, 0x3ff, v49
	v_lshl_add_u32 v229, v229, 2, s97
	v_cndmask_b32_e32 v229, v231, v229, vcc
	ds_add_u32 v229, v176 offset:41984
	v_lshrrev_b32_e32 v129, 10, v48
	v_cmp_eq_u32_e32 vcc, s55, v129
	v_and_b32_e32 v229, 0x3ff, v48
	v_lshl_add_u32 v229, v229, 2, s97
	v_cndmask_b32_e32 v229, v231, v229, vcc
	ds_add_u32 v229, v176 offset:41984
	v_lshrrev_b32_e32 v129, 10, v46
	v_cmp_eq_u32_e32 vcc, s55, v129
	v_and_b32_e32 v229, 0x3ff, v46
	v_lshl_add_u32 v229, v229, 2, s97
	v_cndmask_b32_e32 v229, v231, v229, vcc
	ds_add_u32 v229, v176 offset:41984
	v_lshrrev_b32_e32 v129, 10, v45
	v_cmp_eq_u32_e32 vcc, s55, v129
	v_and_b32_e32 v229, 0x3ff, v45
	v_lshl_add_u32 v229, v229, 2, s97
	v_cndmask_b32_e32 v229, v231, v229, vcc
	ds_add_u32 v229, v176 offset:41984
	v_lshrrev_b32_e32 v129, 10, v44
	v_cmp_eq_u32_e32 vcc, s55, v129
	v_and_b32_e32 v229, 0x3ff, v44
	v_lshl_add_u32 v229, v229, 2, s97
	v_cndmask_b32_e32 v229, v231, v229, vcc
	ds_add_u32 v229, v176 offset:41984
	v_lshrrev_b32_e32 v129, 10, v43
	v_cmp_eq_u32_e32 vcc, s55, v129
	v_and_b32_e32 v229, 0x3ff, v43
	v_lshl_add_u32 v229, v229, 2, s97
	v_cndmask_b32_e32 v229, v231, v229, vcc
	ds_add_u32 v229, v176 offset:41984
	v_lshrrev_b32_e32 v129, 10, v42
	v_cmp_eq_u32_e32 vcc, s55, v129
	v_and_b32_e32 v229, 0x3ff, v42
	v_lshl_add_u32 v229, v229, 2, s97
	v_cndmask_b32_e32 v229, v231, v229, vcc
	ds_add_u32 v229, v176 offset:41984
	v_lshrrev_b32_e32 v129, 10, v41
	v_cmp_eq_u32_e32 vcc, s55, v129
	v_and_b32_e32 v229, 0x3ff, v41
	v_lshl_add_u32 v229, v229, 2, s97
	v_cndmask_b32_e32 v229, v231, v229, vcc
	ds_add_u32 v229, v176 offset:41984
	v_lshrrev_b32_e32 v129, 10, v40
	v_cmp_eq_u32_e32 vcc, s55, v129
	v_and_b32_e32 v229, 0x3ff, v40
	v_lshl_add_u32 v229, v229, 2, s97
	v_cndmask_b32_e32 v229, v231, v229, vcc
	ds_add_u32 v229, v176 offset:41984
	v_lshrrev_b32_e32 v129, 10, v39
	v_cmp_eq_u32_e32 vcc, s55, v129
	v_and_b32_e32 v229, 0x3ff, v39
	v_lshl_add_u32 v229, v229, 2, s97
	v_cndmask_b32_e32 v229, v231, v229, vcc
	ds_add_u32 v229, v176 offset:41984
	v_lshrrev_b32_e32 v129, 10, v38
	v_cmp_eq_u32_e32 vcc, s55, v129
	v_and_b32_e32 v229, 0x3ff, v38
	v_lshl_add_u32 v229, v229, 2, s97
	v_cndmask_b32_e32 v229, v231, v229, vcc
	ds_add_u32 v229, v176 offset:41984
	v_lshrrev_b32_e32 v129, 10, v37
	v_cmp_eq_u32_e32 vcc, s55, v129
	v_and_b32_e32 v229, 0x3ff, v37
	v_lshl_add_u32 v229, v229, 2, s97
	v_cndmask_b32_e32 v229, v231, v229, vcc
	ds_add_u32 v229, v176 offset:41984
	v_lshrrev_b32_e32 v129, 10, v36
	v_cmp_eq_u32_e32 vcc, s55, v129
	v_and_b32_e32 v229, 0x3ff, v36
	v_lshl_add_u32 v229, v229, 2, s97
	v_cndmask_b32_e32 v229, v231, v229, vcc
	ds_add_u32 v229, v176 offset:41984
	v_lshrrev_b32_e32 v129, 10, v35
	v_cmp_eq_u32_e32 vcc, s55, v129
	v_and_b32_e32 v229, 0x3ff, v35
	v_lshl_add_u32 v229, v229, 2, s97
	v_cndmask_b32_e32 v229, v231, v229, vcc
	ds_add_u32 v229, v176 offset:41984
	v_lshrrev_b32_e32 v129, 10, v33
	v_cmp_eq_u32_e32 vcc, s55, v129
	v_and_b32_e32 v229, 0x3ff, v33
	v_lshl_add_u32 v229, v229, 2, s97
	v_cndmask_b32_e32 v229, v231, v229, vcc
	ds_add_u32 v229, v176 offset:41984
	s_and_b64 vcc, exec, s[36:37]
	s_cbranch_vccnz .LBB0_646
; template <int SHIFT, int NBITS, bool FIRST>
; __device__ __forceinline__ void radix_pass(const unsigned (&uu)[128], int nreg, unsigned* hist, int lane, unsigned& prefix, int& need) {
;     ...
;     for (int g = 0; g < 8; ++g) {
;         if (g * 16 < nreg) {
; #pragma unroll
;             for (int r = g * 16; r < g * 16 + 16; ++r) {
;                 const unsigned u = uu[r];
;                 const bool match = FIRST ? true : ((u >> (SHIFT + NBITS)) == prefix);
;                 if (match) __hip_atomic_fetch_add(hist + ((u >> SHIFT) & (NBINS - 1)), 1u, __ATOMIC_RELAXED, __HIP_MEMORY_SCOPE_WORKGROUP);
;             }
;         }
;     }
.LBB0_813:
	v_lshrrev_b32_e32 v129, 10, v34
	v_cmp_eq_u32_e32 vcc, s55, v129
	v_and_b32_e32 v229, 0x3ff, v34
	v_lshl_add_u32 v229, v229, 2, s97
	v_cndmask_b32_e32 v229, v231, v229, vcc
	ds_add_u32 v229, v176 offset:41984
	v_lshrrev_b32_e32 v129, 10, v32
	v_cmp_eq_u32_e32 vcc, s55, v129
	v_and_b32_e32 v229, 0x3ff, v32
	v_lshl_add_u32 v229, v229, 2, s97
	v_cndmask_b32_e32 v229, v231, v229, vcc
	ds_add_u32 v229, v176 offset:41984
	v_lshrrev_b32_e32 v129, 10, v31
	v_cmp_eq_u32_e32 vcc, s55, v129
	v_and_b32_e32 v229, 0x3ff, v31
	v_lshl_add_u32 v229, v229, 2, s97
	v_cndmask_b32_e32 v229, v231, v229, vcc
	ds_add_u32 v229, v176 offset:41984
	v_lshrrev_b32_e32 v129, 10, v30
	v_cmp_eq_u32_e32 vcc, s55, v129
	v_and_b32_e32 v229, 0x3ff, v30
	v_lshl_add_u32 v229, v229, 2, s97
	v_cndmask_b32_e32 v229, v231, v229, vcc
	ds_add_u32 v229, v176 offset:41984
	v_lshrrev_b32_e32 v129, 10, v29
	v_cmp_eq_u32_e32 vcc, s55, v129
	v_and_b32_e32 v229, 0x3ff, v29
	v_lshl_add_u32 v229, v229, 2, s97
	v_cndmask_b32_e32 v229, v231, v229, vcc
	ds_add_u32 v229, v176 offset:41984
	v_lshrrev_b32_e32 v129, 10, v28
	v_cmp_eq_u32_e32 vcc, s55, v129
	v_and_b32_e32 v229, 0x3ff, v28
	v_lshl_add_u32 v229, v229, 2, s97
	v_cndmask_b32_e32 v229, v231, v229, vcc
	ds_add_u32 v229, v176 offset:41984
	v_lshrrev_b32_e32 v129, 10, v27
	v_cmp_eq_u32_e32 vcc, s55, v129
	v_and_b32_e32 v229, 0x3ff, v27
	v_lshl_add_u32 v229, v229, 2, s97
	v_cndmask_b32_e32 v229, v231, v229, vcc
	ds_add_u32 v229, v176 offset:41984
	v_lshrrev_b32_e32 v129, 10, v26
	v_cmp_eq_u32_e32 vcc, s55, v129
	v_and_b32_e32 v229, 0x3ff, v26
	v_lshl_add_u32 v229, v229, 2, s97
	v_cndmask_b32_e32 v229, v231, v229, vcc
	ds_add_u32 v229, v176 offset:41984
	v_lshrrev_b32_e32 v129, 10, v25
	v_cmp_eq_u32_e32 vcc, s55, v129
	v_and_b32_e32 v229, 0x3ff, v25
	v_lshl_add_u32 v229, v229, 2, s97
	v_cndmask_b32_e32 v229, v231, v229, vcc
	ds_add_u32 v229, v176 offset:41984
	v_lshrrev_b32_e32 v129, 10, v24
	v_cmp_eq_u32_e32 vcc, s55, v129
	v_and_b32_e32 v229, 0x3ff, v24
	v_lshl_add_u32 v229, v229, 2, s97
	v_cndmask_b32_e32 v229, v231, v229, vcc
	ds_add_u32 v229, v176 offset:41984
	v_lshrrev_b32_e32 v129, 10, v23
	v_cmp_eq_u32_e32 vcc, s55, v129
	v_and_b32_e32 v229, 0x3ff, v23
	v_lshl_add_u32 v229, v229, 2, s97
	v_cndmask_b32_e32 v229, v231, v229, vcc
	ds_add_u32 v229, v176 offset:41984
	v_lshrrev_b32_e32 v129, 10, v22
	v_cmp_eq_u32_e32 vcc, s55, v129
	v_and_b32_e32 v229, 0x3ff, v22
	v_lshl_add_u32 v229, v229, 2, s97
	v_cndmask_b32_e32 v229, v231, v229, vcc
	ds_add_u32 v229, v176 offset:41984
	v_lshrrev_b32_e32 v129, 10, v21
	v_cmp_eq_u32_e32 vcc, s55, v129
	v_and_b32_e32 v229, 0x3ff, v21
	v_lshl_add_u32 v229, v229, 2, s97
	v_cndmask_b32_e32 v229, v231, v229, vcc
	ds_add_u32 v229, v176 offset:41984
	v_lshrrev_b32_e32 v129, 10, v20
	v_cmp_eq_u32_e32 vcc, s55, v129
	v_and_b32_e32 v229, 0x3ff, v20
	v_lshl_add_u32 v229, v229, 2, s97
	v_cndmask_b32_e32 v229, v231, v229, vcc
	ds_add_u32 v229, v176 offset:41984
	v_lshrrev_b32_e32 v129, 10, v19
	v_cmp_eq_u32_e32 vcc, s55, v129
	v_and_b32_e32 v229, 0x3ff, v19
	v_lshl_add_u32 v229, v229, 2, s97
	v_cndmask_b32_e32 v229, v231, v229, vcc
	ds_add_u32 v229, v176 offset:41984
	v_lshrrev_b32_e32 v129, 10, v15
	v_cmp_eq_u32_e32 vcc, s55, v129
	v_and_b32_e32 v229, 0x3ff, v15
	v_lshl_add_u32 v229, v229, 2, s97
	v_cndmask_b32_e32 v229, v231, v229, vcc
	ds_add_u32 v229, v176 offset:41984
	s_and_b64 vcc, exec, s[38:39]
	s_cbranch_vccnz .LBB0_879
.LBB0_846:
	v_lshrrev_b32_e32 v129, 10, v18
	v_cmp_eq_u32_e32 vcc, s55, v129
	v_and_b32_e32 v229, 0x3ff, v18
	v_lshl_add_u32 v229, v229, 2, s97
	v_cndmask_b32_e32 v229, v231, v229, vcc
	ds_add_u32 v229, v176 offset:41984
	v_lshrrev_b32_e32 v129, 10, v17
	v_cmp_eq_u32_e32 vcc, s55, v129
	v_and_b32_e32 v229, 0x3ff, v17
	v_lshl_add_u32 v229, v229, 2, s97
	v_cndmask_b32_e32 v229, v231, v229, vcc
	ds_add_u32 v229, v176 offset:41984
	v_lshrrev_b32_e32 v129, 10, v16
	v_cmp_eq_u32_e32 vcc, s55, v129
	v_and_b32_e32 v229, 0x3ff, v16
	v_lshl_add_u32 v229, v229, 2, s97
	v_cndmask_b32_e32 v229, v231, v229, vcc
	ds_add_u32 v229, v176 offset:41984
	v_lshrrev_b32_e32 v129, 10, v14
	v_cmp_eq_u32_e32 vcc, s55, v129
	v_and_b32_e32 v229, 0x3ff, v14
	v_lshl_add_u32 v229, v229, 2, s97
	v_cndmask_b32_e32 v229, v231, v229, vcc
	ds_add_u32 v229, v176 offset:41984
	v_lshrrev_b32_e32 v129, 10, v13
	v_cmp_eq_u32_e32 vcc, s55, v129
	v_and_b32_e32 v229, 0x3ff, v13
	v_lshl_add_u32 v229, v229, 2, s97
	v_cndmask_b32_e32 v229, v231, v229, vcc
	ds_add_u32 v229, v176 offset:41984
	v_lshrrev_b32_e32 v129, 10, v12
	v_cmp_eq_u32_e32 vcc, s55, v129
	v_and_b32_e32 v229, 0x3ff, v12
	v_lshl_add_u32 v229, v229, 2, s97
	v_cndmask_b32_e32 v229, v231, v229, vcc
	ds_add_u32 v229, v176 offset:41984
	v_lshrrev_b32_e32 v129, 10, v11
	v_cmp_eq_u32_e32 vcc, s55, v129
	v_and_b32_e32 v229, 0x3ff, v11
	v_lshl_add_u32 v229, v229, 2, s97
	v_cndmask_b32_e32 v229, v231, v229, vcc
	ds_add_u32 v229, v176 offset:41984
	v_lshrrev_b32_e32 v129, 10, v10
	v_cmp_eq_u32_e32 vcc, s55, v129
	v_and_b32_e32 v229, 0x3ff, v10
	v_lshl_add_u32 v229, v229, 2, s97
	v_cndmask_b32_e32 v229, v231, v229, vcc
	ds_add_u32 v229, v176 offset:41984
	v_lshrrev_b32_e32 v129, 10, v9
	v_cmp_eq_u32_e32 vcc, s55, v129
	v_and_b32_e32 v229, 0x3ff, v9
	v_lshl_add_u32 v229, v229, 2, s97
	v_cndmask_b32_e32 v229, v231, v229, vcc
	ds_add_u32 v229, v176 offset:41984
	v_lshrrev_b32_e32 v129, 10, v8
	v_cmp_eq_u32_e32 vcc, s55, v129
	v_and_b32_e32 v229, 0x3ff, v8
	v_lshl_add_u32 v229, v229, 2, s97
	v_cndmask_b32_e32 v229, v231, v229, vcc
	ds_add_u32 v229, v176 offset:41984
	v_lshrrev_b32_e32 v129, 10, v7
	v_cmp_eq_u32_e32 vcc, s55, v129
	v_and_b32_e32 v229, 0x3ff, v7
	v_lshl_add_u32 v229, v229, 2, s97
	v_cndmask_b32_e32 v229, v231, v229, vcc
	ds_add_u32 v229, v176 offset:41984
	v_lshrrev_b32_e32 v129, 10, v6
	v_cmp_eq_u32_e32 vcc, s55, v129
	v_and_b32_e32 v229, 0x3ff, v6
	v_lshl_add_u32 v229, v229, 2, s97
	v_cndmask_b32_e32 v229, v231, v229, vcc
	ds_add_u32 v229, v176 offset:41984
	v_lshrrev_b32_e32 v129, 10, v5
	v_cmp_eq_u32_e32 vcc, s55, v129
	v_and_b32_e32 v229, 0x3ff, v5
	v_lshl_add_u32 v229, v229, 2, s97
	v_cndmask_b32_e32 v229, v231, v229, vcc
	ds_add_u32 v229, v176 offset:41984
	v_lshrrev_b32_e32 v129, 10, v4
	v_cmp_eq_u32_e32 vcc, s55, v129
	v_and_b32_e32 v229, 0x3ff, v4
	v_lshl_add_u32 v229, v229, 2, s97
	v_cndmask_b32_e32 v229, v231, v229, vcc
	ds_add_u32 v229, v176 offset:41984
	v_lshrrev_b32_e32 v129, 10, v3
	v_cmp_eq_u32_e32 vcc, s55, v129
	v_and_b32_e32 v229, 0x3ff, v3
	v_lshl_add_u32 v229, v229, 2, s97
	v_cndmask_b32_e32 v229, v231, v229, vcc
	ds_add_u32 v229, v176 offset:41984
	v_lshrrev_b32_e32 v129, 10, v2
	v_cmp_eq_u32_e32 vcc, s55, v129
	v_and_b32_e32 v229, 0x3ff, v2
	v_lshl_add_u32 v229, v229, 2, s97
	v_cndmask_b32_e32 v229, v231, v229, vcc
	ds_add_u32 v229, v176 offset:41984
